# GEMM K-loops: one static s_setprio 1 for the younger half (waves 4-7) per loop instead of per-segment priority flips
# speedup vs baseline: 1.0062x; 1.0027x over previous
.LBB0_292:
	s_add_u32 s19, s40, 0x100
	s_addc_u32 s54, s41, 0
	s_add_u32 s55, s38, 0x100
	v_mov_b32_e32 v2, 0
	s_addc_u32 s56, s39, 0
	s_mov_b32 s57, -2
	v_mov_b32_e32 v3, v2
	v_mov_b32_e32 v4, v2
	v_mov_b32_e32 v5, v2
	v_mov_b32_e32 v6, v2
	v_mov_b32_e32 v7, v2
	v_mov_b32_e32 v8, v2
	v_mov_b32_e32 v9, v2
	s_waitcnt vmcnt(0)
	v_mov_b32_e32 v18, v2
	v_mov_b32_e32 v19, v2
	v_mov_b32_e32 v20, v2
	v_mov_b32_e32 v21, v2
	v_mov_b32_e32 v22, v2
	v_mov_b32_e32 v23, v2
	v_mov_b32_e32 v24, v2
	v_mov_b32_e32 v25, v2
	v_mov_b32_e32 v34, v2
	v_mov_b32_e32 v35, v2
	v_mov_b32_e32 v36, v2
	v_mov_b32_e32 v37, v2
	v_mov_b32_e32 v38, v2
	v_mov_b32_e32 v39, v2
	v_mov_b32_e32 v40, v2
	v_mov_b32_e32 v41, v2
	v_mov_b32_e32 v58, v2
	v_mov_b32_e32 v59, v2
	v_mov_b32_e32 v60, v2
	v_mov_b32_e32 v61, v2
	v_mov_b32_e32 v62, v2
	v_mov_b32_e32 v63, v2
	v_mov_b32_e32 v64, v2
	v_mov_b32_e32 v65, v2
	v_mov_b32_e32 v10, v2
	v_mov_b32_e32 v11, v2
	v_mov_b32_e32 v12, v2
	v_mov_b32_e32 v13, v2
	v_mov_b32_e32 v14, v2
	v_mov_b32_e32 v15, v2
	v_mov_b32_e32 v16, v2
	v_mov_b32_e32 v17, v2
	v_mov_b32_e32 v26, v2
	v_mov_b32_e32 v27, v2
	v_mov_b32_e32 v28, v2
	v_mov_b32_e32 v29, v2
	v_mov_b32_e32 v30, v2
	v_mov_b32_e32 v31, v2
	v_mov_b32_e32 v32, v2
	v_mov_b32_e32 v33, v2
	v_mov_b32_e32 v50, v2
	v_mov_b32_e32 v51, v2
	v_mov_b32_e32 v52, v2
	v_mov_b32_e32 v53, v2
	v_mov_b32_e32 v54, v2
	v_mov_b32_e32 v55, v2
	v_mov_b32_e32 v56, v2
	v_mov_b32_e32 v57, v2
	v_mov_b32_e32 v74, v2
	v_mov_b32_e32 v75, v2
	v_mov_b32_e32 v76, v2
	v_mov_b32_e32 v77, v2
	v_mov_b32_e32 v78, v2
	v_mov_b32_e32 v79, v2
	v_mov_b32_e32 v80, v2
	v_mov_b32_e32 v81, v2
	v_mov_b32_e32 v82, v2
	v_mov_b32_e32 v83, v2
	v_mov_b32_e32 v84, v2
	v_mov_b32_e32 v85, v2
	v_mov_b32_e32 v94, v2
	v_mov_b32_e32 v95, v2
	v_mov_b32_e32 v96, v2
	v_mov_b32_e32 v97, v2
	v_mov_b32_e32 v114, v2
	v_mov_b32_e32 v115, v2
	v_mov_b32_e32 v116, v2
	v_mov_b32_e32 v117, v2
	v_mov_b32_e32 v118, v2
	v_mov_b32_e32 v119, v2
	v_mov_b32_e32 v120, v2
	v_mov_b32_e32 v121, v2
	v_mov_b32_e32 v138, v2
	v_mov_b32_e32 v139, v2
	v_mov_b32_e32 v140, v2
	v_mov_b32_e32 v141, v2
	v_mov_b32_e32 v142, v2
	v_mov_b32_e32 v143, v2
	v_mov_b32_e32 v144, v2
	v_mov_b32_e32 v145, v2
	v_mov_b32_e32 v162, v2
	v_mov_b32_e32 v163, v2
	v_mov_b32_e32 v164, v2
	v_mov_b32_e32 v165, v2
	v_mov_b32_e32 v166, v2
	v_mov_b32_e32 v167, v2
	v_mov_b32_e32 v168, v2
	v_mov_b32_e32 v169, v2
	v_mov_b32_e32 v98, v2
	v_mov_b32_e32 v99, v2
	v_mov_b32_e32 v100, v2
	v_mov_b32_e32 v101, v2
	v_mov_b32_e32 v102, v2
	v_mov_b32_e32 v103, v2
	v_mov_b32_e32 v104, v2
	v_mov_b32_e32 v105, v2
	v_mov_b32_e32 v122, v2
	v_mov_b32_e32 v123, v2
	v_mov_b32_e32 v124, v2
	v_mov_b32_e32 v125, v2
	v_mov_b32_e32 v126, v2
	v_mov_b32_e32 v127, v2
	v_mov_b32_e32 v128, v2
	v_mov_b32_e32 v129, v2
	v_mov_b32_e32 v146, v2
	v_mov_b32_e32 v147, v2
	v_mov_b32_e32 v148, v2
	v_mov_b32_e32 v149, v2
	v_mov_b32_e32 v150, v2
	v_mov_b32_e32 v151, v2
	v_mov_b32_e32 v152, v2
	v_mov_b32_e32 v153, v2
	v_mov_b32_e32 v170, v2
	v_mov_b32_e32 v171, v2
	v_mov_b32_e32 v172, v2
	v_mov_b32_e32 v173, v2
	v_mov_b32_e32 v174, v2
	v_mov_b32_e32 v175, v2
	v_mov_b32_e32 v176, v2
	v_mov_b32_e32 v177, v2
	s_cmp_lg_u32 s16, 0
	s_cbranch_scc1 .Lsp0
	s_setprio 1
.Lsp0:
.LBB0_293:
	s_cmp_eq_u32 s57, 28
	s_cselect_b32 s42, s10, s19
	s_cselect_b32 s43, s11, s54
	s_cselect_b32 s40, s26, s55
	s_cselect_b32 s41, s27, s56
	s_cbranch_scc0 .Lip_nopf
	s_lshl_b32 s58, s29, 13
	s_add_u32 s58, s14, s58
	s_addc_u32 s59, s15, 0
	v_mbcnt_lo_u32_b32 v250, -1, 0
	v_mbcnt_hi_u32_b32 v250, -1, v250
	v_lshl_add_u32 v250, v250, 4, s46
	s_add_i32 m0, s46, 0x24f80
	s_nop 0
	global_load_lds_dwordx4 v250, s[58:59]
.Lip_nopf:
	s_add_u32 s38, s42, 0x80
	s_addc_u32 s39, s43, 0
	s_add_i32 s60, 0, 0x10000
	s_add_i32 s61, 0, 0x14000
	v_add_u32_e32 v70, s60, v207
	v_add_u32_e32 v110, s61, v207
	ds_read_b128 v[42:45], v70
	ds_read_b128 v[46:49], v70 offset:1024
	ds_read_b128 v[66:69], v70 offset:2048
	ds_read_b128 v[70:73], v70 offset:3072
	ds_read_b128 v[86:89], v110
	ds_read_b128 v[90:93], v110 offset:1024
	ds_read_b128 v[106:109], v110 offset:2048
	ds_read_b128 v[110:113], v110 offset:3072
	s_add_u32 s58, s19, 0x7ff80
	s_addc_u32 s59, s54, 0
	ds_read_b128 v[130:133], v237
	ds_read_b128 v[134:137], v237 offset:1024
	ds_read_b128 v[154:157], v237 offset:2048
	ds_read_b128 v[158:161], v237 offset:3072
	ds_read_b128 v[178:181], v237 offset:4096
	ds_read_b128 v[182:185], v237 offset:5120
	ds_read_b128 v[186:189], v237 offset:6144
	ds_read_b128 v[190:193], v237 offset:7168
	s_add_i32 m0, s46, 0xc000
	v_lshl_add_u64 v[194:195], s[58:59], 0, v[208:209]
	s_add_u32 s58, s58, 0x40000
	s_addc_u32 s59, s59, 0
	global_load_lds_dwordx4 v[194:195], off
	s_add_i32 m0, s46, 0xe000
	v_lshl_add_u64 v[194:195], s[58:59], 0, v[208:209]
	global_load_lds_dwordx4 v[194:195], off
	s_waitcnt vmcnt(8)
	s_waitcnt lgkmcnt(0)
	s_barrier
	s_waitcnt lgkmcnt(0)
	v_mfma_f32_16x16x32_bf16 v[174:177], v[42:45], v[130:133], v[174:177]
	v_mfma_f32_16x16x32_bf16 v[170:173], v[66:69], v[130:133], v[170:173]
	v_mfma_f32_16x16x32_bf16 v[150:153], v[42:45], v[154:157], v[150:153]
	v_mfma_f32_16x16x32_bf16 v[146:149], v[66:69], v[154:157], v[146:149]
	v_mfma_f32_16x16x32_bf16 v[126:129], v[42:45], v[178:181], v[126:129]
	v_mfma_f32_16x16x32_bf16 v[122:125], v[66:69], v[178:181], v[122:125]
	v_mfma_f32_16x16x32_bf16 v[102:105], v[42:45], v[186:189], v[102:105]
	v_mfma_f32_16x16x32_bf16 v[98:101], v[66:69], v[186:189], v[98:101]
	v_mfma_f32_16x16x32_bf16 v[174:177], v[46:49], v[134:137], v[174:177]
	v_mfma_f32_16x16x32_bf16 v[170:173], v[70:73], v[134:137], v[170:173]
	v_mfma_f32_16x16x32_bf16 v[150:153], v[46:49], v[158:161], v[150:153]
	v_mfma_f32_16x16x32_bf16 v[146:149], v[70:73], v[158:161], v[146:149]
	v_mfma_f32_16x16x32_bf16 v[126:129], v[46:49], v[182:185], v[126:129]
	v_mfma_f32_16x16x32_bf16 v[122:125], v[70:73], v[182:185], v[122:125]
	v_mfma_f32_16x16x32_bf16 v[102:105], v[46:49], v[190:193], v[102:105]
	v_mfma_f32_16x16x32_bf16 v[98:101], v[70:73], v[190:193], v[98:101]
	v_mfma_f32_16x16x32_bf16 v[166:169], v[86:89], v[130:133], v[166:169]
	v_mfma_f32_16x16x32_bf16 v[130:133], v[106:109], v[130:133], v[162:165]
	v_mfma_f32_16x16x32_bf16 v[138:141], v[106:109], v[154:157], v[138:141]
	v_mfma_f32_16x16x32_bf16 v[118:121], v[86:89], v[178:181], v[118:121]
	v_mfma_f32_16x16x32_bf16 v[114:117], v[106:109], v[178:181], v[114:117]
	v_mfma_f32_16x16x32_bf16 v[94:97], v[86:89], v[186:189], v[94:97]
	v_mfma_f32_16x16x32_bf16 v[82:85], v[106:109], v[186:189], v[82:85]
	v_mfma_f32_16x16x32_bf16 v[166:169], v[90:93], v[134:137], v[166:169]
	v_mfma_f32_16x16x32_bf16 v[130:133], v[110:113], v[134:137], v[130:133]
	v_mfma_f32_16x16x32_bf16 v[134:137], v[86:89], v[154:157], v[142:145]
	v_mfma_f32_16x16x32_bf16 v[138:141], v[110:113], v[158:161], v[138:141]
	v_mfma_f32_16x16x32_bf16 v[118:121], v[90:93], v[182:185], v[118:121]
	v_mfma_f32_16x16x32_bf16 v[114:117], v[110:113], v[182:185], v[114:117]
	v_mfma_f32_16x16x32_bf16 v[94:97], v[90:93], v[190:193], v[94:97]
	v_mfma_f32_16x16x32_bf16 v[82:85], v[110:113], v[190:193], v[82:85]
	v_mfma_f32_16x16x32_bf16 v[134:137], v[90:93], v[158:161], v[134:137]
	s_barrier
	s_mov_b64 s[58:59], s[40:41]
	ds_read_b128 v[142:145], v237 offset:16384
	ds_read_b128 v[154:157], v237 offset:17408
	ds_read_b128 v[158:161], v237 offset:18432
	ds_read_b128 v[162:165], v237 offset:19456
	ds_read_b128 v[178:181], v237 offset:20480
	ds_read_b128 v[182:185], v237 offset:21504
	ds_read_b128 v[186:189], v237 offset:22528
	ds_read_b128 v[190:193], v237 offset:23552
	s_add_i32 s60, s60, s45
	v_lshl_add_u64 v[194:195], s[58:59], 0, v[202:203]
	s_add_u32 s58, s58, 0x40000
	s_mov_b32 m0, s60
	s_addc_u32 s59, s59, 0
	global_load_lds_dwordx4 v[194:195], off
	s_add_i32 m0, s60, 0x2000
	v_lshl_add_u64 v[194:195], s[58:59], 0, v[202:203]
	s_add_u32 s58, s40, 0x80000
	s_addc_u32 s59, s41, 0
	global_load_lds_dwordx4 v[194:195], off
	s_add_i32 s60, s61, s45
	v_lshl_add_u64 v[194:195], s[58:59], 0, v[202:203]
	s_add_u32 s58, s58, 0x40000
	s_mov_b32 m0, s60
	s_addc_u32 s59, s59, 0
	global_load_lds_dwordx4 v[194:195], off
	s_add_i32 m0, s60, 0x2000
	v_lshl_add_u64 v[194:195], s[58:59], 0, v[202:203]
	s_mov_b64 s[58:59], s[42:43]
	global_load_lds_dwordx4 v[194:195], off
	s_mov_b32 m0, s46
	v_lshl_add_u64 v[194:195], s[58:59], 0, v[208:209]
	s_add_u32 s58, s58, 0x40000
	s_addc_u32 s59, s59, 0
	global_load_lds_dwordx4 v[194:195], off
	s_mov_b32 m0, s47
	v_lshl_add_u64 v[194:195], s[58:59], 0, v[208:209]
	global_load_lds_dwordx4 v[194:195], off
	s_waitcnt vmcnt(8)
	s_waitcnt lgkmcnt(0)
	s_barrier
	s_waitcnt lgkmcnt(0)
	v_mfma_f32_16x16x32_bf16 v[78:81], v[42:45], v[142:145], v[78:81]
	v_mfma_f32_16x16x32_bf16 v[74:77], v[66:69], v[142:145], v[74:77]
	v_mfma_f32_16x16x32_bf16 v[54:57], v[42:45], v[158:161], v[54:57]
	v_mfma_f32_16x16x32_bf16 v[50:53], v[66:69], v[158:161], v[50:53]
	v_mfma_f32_16x16x32_bf16 v[30:33], v[42:45], v[178:181], v[30:33]
	v_mfma_f32_16x16x32_bf16 v[26:29], v[66:69], v[178:181], v[26:29]
	v_mfma_f32_16x16x32_bf16 v[14:17], v[42:45], v[186:189], v[14:17]
	v_mfma_f32_16x16x32_bf16 v[10:13], v[66:69], v[186:189], v[10:13]
	v_mfma_f32_16x16x32_bf16 v[78:81], v[46:49], v[154:157], v[78:81]
	v_mfma_f32_16x16x32_bf16 v[74:77], v[70:73], v[154:157], v[74:77]
	v_mfma_f32_16x16x32_bf16 v[54:57], v[46:49], v[162:165], v[54:57]
	v_mfma_f32_16x16x32_bf16 v[50:53], v[70:73], v[162:165], v[50:53]
	v_mfma_f32_16x16x32_bf16 v[30:33], v[46:49], v[182:185], v[30:33]
	v_mfma_f32_16x16x32_bf16 v[26:29], v[70:73], v[182:185], v[26:29]
	v_mfma_f32_16x16x32_bf16 v[14:17], v[46:49], v[190:193], v[14:17]
	v_mfma_f32_16x16x32_bf16 v[10:13], v[70:73], v[190:193], v[10:13]
	v_mfma_f32_16x16x32_bf16 v[38:41], v[86:89], v[158:161], v[38:41]
	v_mfma_f32_16x16x32_bf16 v[34:37], v[106:109], v[158:161], v[34:37]
	v_mfma_f32_16x16x32_bf16 v[22:25], v[86:89], v[178:181], v[22:25]
	v_mfma_f32_16x16x32_bf16 v[18:21], v[106:109], v[178:181], v[18:21]
	v_mfma_f32_16x16x32_bf16 v[6:9], v[86:89], v[186:189], v[6:9]
	v_mfma_f32_16x16x32_bf16 v[2:5], v[106:109], v[186:189], v[2:5]
	v_mfma_f32_16x16x32_bf16 v[42:45], v[86:89], v[142:145], v[62:65]
	v_mfma_f32_16x16x32_bf16 v[46:49], v[106:109], v[142:145], v[58:61]
	v_mfma_f32_16x16x32_bf16 v[38:41], v[90:93], v[162:165], v[38:41]
	v_mfma_f32_16x16x32_bf16 v[34:37], v[110:113], v[162:165], v[34:37]
	v_mfma_f32_16x16x32_bf16 v[22:25], v[90:93], v[182:185], v[22:25]
	v_mfma_f32_16x16x32_bf16 v[18:21], v[110:113], v[182:185], v[18:21]
	v_mfma_f32_16x16x32_bf16 v[6:9], v[90:93], v[190:193], v[6:9]
	v_mfma_f32_16x16x32_bf16 v[2:5], v[110:113], v[190:193], v[2:5]
	v_mfma_f32_16x16x32_bf16 v[42:45], v[90:93], v[154:157], v[42:45]
	v_mfma_f32_16x16x32_bf16 v[46:49], v[110:113], v[154:157], v[46:49]
	s_barrier
	s_add_i32 s58, 0, 0x18000
	s_add_i32 s59, 0, 0x1c000
	v_add_u32_e32 v70, s58, v207
	v_add_u32_e32 v110, s59, v207
	ds_read_b128 v[58:61], v70
	ds_read_b128 v[62:65], v70 offset:1024
	ds_read_b128 v[66:69], v70 offset:2048
	ds_read_b128 v[70:73], v70 offset:3072
	ds_read_b128 v[86:89], v110
	ds_read_b128 v[90:93], v110 offset:1024
	ds_read_b128 v[106:109], v110 offset:2048
	ds_read_b128 v[110:113], v110 offset:3072
	s_add_u32 s42, s42, 0x80000
	s_addc_u32 s43, s43, 0
	ds_read_b128 v[142:145], v237 offset:32768
	ds_read_b128 v[154:157], v237 offset:33792
	ds_read_b128 v[158:161], v237 offset:34816
	ds_read_b128 v[178:181], v237 offset:35840
	ds_read_b128 v[182:185], v237 offset:36864
	ds_read_b128 v[186:189], v237 offset:37888
	ds_read_b128 v[190:193], v237 offset:38912
	ds_read_b128 v[194:197], v237 offset:39936
	s_mov_b32 m0, s48
	v_lshl_add_u64 v[162:163], s[42:43], 0, v[208:209]
	s_add_u32 s42, s42, 0x40000
	s_addc_u32 s43, s43, 0
	global_load_lds_dwordx4 v[162:163], off
	s_mov_b32 m0, s49
	v_lshl_add_u64 v[162:163], s[42:43], 0, v[208:209]
	global_load_lds_dwordx4 v[162:163], off
	s_waitcnt vmcnt(8)
	s_waitcnt lgkmcnt(0)
	s_barrier
	s_waitcnt lgkmcnt(0)
	v_mfma_f32_16x16x32_bf16 v[162:165], v[58:61], v[142:145], v[174:177]
	v_mfma_f32_16x16x32_bf16 v[174:177], v[62:65], v[154:157], v[162:165]
	v_mfma_f32_16x16x32_bf16 v[162:165], v[66:69], v[142:145], v[170:173]
	v_mfma_f32_16x16x32_bf16 v[150:153], v[58:61], v[158:161], v[150:153]
	v_mfma_f32_16x16x32_bf16 v[146:149], v[66:69], v[158:161], v[146:149]
	v_mfma_f32_16x16x32_bf16 v[126:129], v[58:61], v[182:185], v[126:129]
	v_mfma_f32_16x16x32_bf16 v[122:125], v[66:69], v[182:185], v[122:125]
	v_mfma_f32_16x16x32_bf16 v[102:105], v[58:61], v[190:193], v[102:105]
	v_mfma_f32_16x16x32_bf16 v[98:101], v[66:69], v[190:193], v[98:101]
	v_mfma_f32_16x16x32_bf16 v[170:173], v[70:73], v[154:157], v[162:165]
	v_mfma_f32_16x16x32_bf16 v[150:153], v[62:65], v[178:181], v[150:153]
	v_mfma_f32_16x16x32_bf16 v[146:149], v[70:73], v[178:181], v[146:149]
	v_mfma_f32_16x16x32_bf16 v[126:129], v[62:65], v[186:189], v[126:129]
	v_mfma_f32_16x16x32_bf16 v[122:125], v[70:73], v[186:189], v[122:125]
	v_mfma_f32_16x16x32_bf16 v[102:105], v[62:65], v[194:197], v[102:105]
	v_mfma_f32_16x16x32_bf16 v[98:101], v[70:73], v[194:197], v[98:101]
	v_mfma_f32_16x16x32_bf16 v[162:165], v[86:89], v[142:145], v[166:169]
	v_mfma_f32_16x16x32_bf16 v[130:133], v[106:109], v[142:145], v[130:133]
	v_mfma_f32_16x16x32_bf16 v[166:169], v[90:93], v[154:157], v[162:165]
	v_mfma_f32_16x16x32_bf16 v[162:165], v[110:113], v[154:157], v[130:133]
	v_mfma_f32_16x16x32_bf16 v[130:133], v[86:89], v[158:161], v[134:137]
	v_mfma_f32_16x16x32_bf16 v[142:145], v[90:93], v[178:181], v[130:133]
	v_mfma_f32_16x16x32_bf16 v[130:133], v[106:109], v[158:161], v[138:141]
	v_mfma_f32_16x16x32_bf16 v[118:121], v[86:89], v[182:185], v[118:121]
	v_mfma_f32_16x16x32_bf16 v[114:117], v[106:109], v[182:185], v[114:117]
	v_mfma_f32_16x16x32_bf16 v[94:97], v[86:89], v[190:193], v[94:97]
	v_mfma_f32_16x16x32_bf16 v[82:85], v[106:109], v[190:193], v[82:85]
	v_mfma_f32_16x16x32_bf16 v[138:141], v[110:113], v[178:181], v[130:133]
	v_mfma_f32_16x16x32_bf16 v[118:121], v[90:93], v[186:189], v[118:121]
	v_mfma_f32_16x16x32_bf16 v[114:117], v[110:113], v[186:189], v[114:117]
	v_mfma_f32_16x16x32_bf16 v[94:97], v[90:93], v[194:197], v[94:97]
	v_mfma_f32_16x16x32_bf16 v[82:85], v[110:113], v[194:197], v[82:85]
	s_barrier
	s_add_u32 s42, s40, 0x80
	s_addc_u32 s43, s41, 0
	ds_read_b128 v[130:133], v237 offset:49152
	ds_read_b128 v[134:137], v237 offset:50176
	ds_read_b128 v[154:157], v237 offset:51200
	ds_read_b128 v[158:161], v237 offset:52224
	ds_read_b128 v[178:181], v237 offset:53248
	ds_read_b128 v[182:185], v237 offset:54272
	ds_read_b128 v[186:189], v237 offset:55296
	ds_read_b128 v[190:193], v237 offset:56320
	s_add_i32 s58, s58, s45
	v_lshl_add_u64 v[194:195], s[42:43], 0, v[202:203]
	s_mov_b32 m0, s58
	s_add_u32 s42, s42, 0x40000
	global_load_lds_dwordx4 v[194:195], off
	s_addc_u32 s43, s43, 0
	s_add_i32 m0, s58, 0x2000
	s_add_u32 s40, s40, 0x80080
	s_addc_u32 s41, s41, 0
	v_lshl_add_u64 v[194:195], s[42:43], 0, v[202:203]
	global_load_lds_dwordx4 v[194:195], off
	s_add_i32 s42, s59, s45
	v_lshl_add_u64 v[194:195], s[40:41], 0, v[202:203]
	s_add_u32 s40, s40, 0x40000
	s_mov_b32 m0, s42
	s_addc_u32 s41, s41, 0
	global_load_lds_dwordx4 v[194:195], off
	s_add_i32 m0, s42, 0x2000
	v_lshl_add_u64 v[194:195], s[40:41], 0, v[202:203]
	global_load_lds_dwordx4 v[194:195], off
	s_mov_b32 m0, s50
	v_lshl_add_u64 v[194:195], s[38:39], 0, v[208:209]
	s_add_u32 s38, s38, 0x40000
	s_addc_u32 s39, s39, 0
	global_load_lds_dwordx4 v[194:195], off
	s_mov_b32 m0, s51
	v_lshl_add_u64 v[194:195], s[38:39], 0, v[208:209]
	global_load_lds_dwordx4 v[194:195], off
	s_waitcnt vmcnt(8)
	s_waitcnt lgkmcnt(0)
	s_barrier
	s_waitcnt lgkmcnt(0)
	v_mfma_f32_16x16x32_bf16 v[78:81], v[58:61], v[130:133], v[78:81]
	v_mfma_f32_16x16x32_bf16 v[74:77], v[66:69], v[130:133], v[74:77]
	v_mfma_f32_16x16x32_bf16 v[54:57], v[58:61], v[154:157], v[54:57]
	v_mfma_f32_16x16x32_bf16 v[50:53], v[66:69], v[154:157], v[50:53]
	v_mfma_f32_16x16x32_bf16 v[30:33], v[58:61], v[178:181], v[30:33]
	v_mfma_f32_16x16x32_bf16 v[26:29], v[66:69], v[178:181], v[26:29]
	v_mfma_f32_16x16x32_bf16 v[14:17], v[58:61], v[186:189], v[14:17]
	v_mfma_f32_16x16x32_bf16 v[10:13], v[66:69], v[186:189], v[10:13]
	v_mfma_f32_16x16x32_bf16 v[78:81], v[62:65], v[134:137], v[78:81]
	v_mfma_f32_16x16x32_bf16 v[74:77], v[70:73], v[134:137], v[74:77]
	v_mfma_f32_16x16x32_bf16 v[54:57], v[62:65], v[158:161], v[54:57]
	v_mfma_f32_16x16x32_bf16 v[50:53], v[70:73], v[158:161], v[50:53]
	v_mfma_f32_16x16x32_bf16 v[30:33], v[62:65], v[182:185], v[30:33]
	v_mfma_f32_16x16x32_bf16 v[26:29], v[70:73], v[182:185], v[26:29]
	v_mfma_f32_16x16x32_bf16 v[14:17], v[62:65], v[190:193], v[14:17]
	v_mfma_f32_16x16x32_bf16 v[10:13], v[70:73], v[190:193], v[10:13]
	v_mfma_f32_16x16x32_bf16 v[42:45], v[86:89], v[130:133], v[42:45]
	v_mfma_f32_16x16x32_bf16 v[62:65], v[90:93], v[134:137], v[42:45]
	v_mfma_f32_16x16x32_bf16 v[42:45], v[106:109], v[130:133], v[46:49]
	v_mfma_f32_16x16x32_bf16 v[38:41], v[86:89], v[154:157], v[38:41]
	v_mfma_f32_16x16x32_bf16 v[34:37], v[106:109], v[154:157], v[34:37]
	v_mfma_f32_16x16x32_bf16 v[22:25], v[86:89], v[178:181], v[22:25]
	v_mfma_f32_16x16x32_bf16 v[18:21], v[106:109], v[178:181], v[18:21]
	v_mfma_f32_16x16x32_bf16 v[6:9], v[86:89], v[186:189], v[6:9]
	v_mfma_f32_16x16x32_bf16 v[2:5], v[106:109], v[186:189], v[2:5]
	v_mfma_f32_16x16x32_bf16 v[58:61], v[110:113], v[134:137], v[42:45]
	v_mfma_f32_16x16x32_bf16 v[38:41], v[90:93], v[158:161], v[38:41]
	v_mfma_f32_16x16x32_bf16 v[34:37], v[110:113], v[158:161], v[34:37]
	v_mfma_f32_16x16x32_bf16 v[22:25], v[90:93], v[182:185], v[22:25]
	v_mfma_f32_16x16x32_bf16 v[18:21], v[110:113], v[182:185], v[18:21]
	v_mfma_f32_16x16x32_bf16 v[6:9], v[90:93], v[190:193], v[6:9]
	v_mfma_f32_16x16x32_bf16 v[2:5], v[110:113], v[190:193], v[2:5]
	s_barrier
	s_add_i32 s57, s57, 2
	s_add_u32 s19, s19, 0x100
	s_addc_u32 s54, s54, 0
	s_add_u32 s55, s55, 0x100
	s_addc_u32 s56, s56, 0
	s_cmp_gt_u32 s57, 29
	s_cbranch_scc0 .LBB0_293
	s_setprio 0
	s_and_b64 vcc, exec, s[16:17]
	s_cbranch_vccz .LBB0_296
	s_barrier

.LBB0_1012:
	s_add_u32 s28, s44, 0x100
	s_addc_u32 s29, s45, 0
	s_add_u32 s76, s10, 0x100
	v_mov_b32_e32 v2, 0
	s_addc_u32 s77, s11, 0
	s_mov_b32 s10, 0
	v_mov_b32_e32 v3, v2
	v_mov_b32_e32 v4, v2
	v_mov_b32_e32 v5, v2
	v_mov_b32_e32 v6, v2
	v_mov_b32_e32 v7, v2
	v_mov_b32_e32 v8, v2
	v_mov_b32_e32 v9, v2
	v_mov_b32_e32 v14, v2
	v_mov_b32_e32 v15, v2
	v_mov_b32_e32 v16, v2
	v_mov_b32_e32 v17, v2
	s_waitcnt vmcnt(0)
	v_mov_b32_e32 v22, v2
	v_mov_b32_e32 v23, v2
	v_mov_b32_e32 v24, v2
	v_mov_b32_e32 v25, v2
	v_mov_b32_e32 v30, v2
	v_mov_b32_e32 v31, v2
	v_mov_b32_e32 v32, v2
	v_mov_b32_e32 v33, v2
	v_mov_b32_e32 v38, v2
	v_mov_b32_e32 v39, v2
	v_mov_b32_e32 v40, v2
	v_mov_b32_e32 v41, v2
	v_mov_b32_e32 v46, v2
	v_mov_b32_e32 v47, v2
	v_mov_b32_e32 v48, v2
	v_mov_b32_e32 v49, v2
	v_mov_b32_e32 v54, v2
	v_mov_b32_e32 v55, v2
	v_mov_b32_e32 v56, v2
	v_mov_b32_e32 v57, v2
	v_mov_b32_e32 v10, v2
	v_mov_b32_e32 v11, v2
	v_mov_b32_e32 v12, v2
	v_mov_b32_e32 v13, v2
	v_mov_b32_e32 v18, v2
	v_mov_b32_e32 v19, v2
	v_mov_b32_e32 v20, v2
	v_mov_b32_e32 v21, v2
	v_mov_b32_e32 v26, v2
	v_mov_b32_e32 v27, v2
	v_mov_b32_e32 v28, v2
	v_mov_b32_e32 v29, v2
	v_mov_b32_e32 v34, v2
	v_mov_b32_e32 v35, v2
	v_mov_b32_e32 v36, v2
	v_mov_b32_e32 v37, v2
	v_mov_b32_e32 v42, v2
	v_mov_b32_e32 v43, v2
	v_mov_b32_e32 v44, v2
	v_mov_b32_e32 v45, v2
	v_mov_b32_e32 v50, v2
	v_mov_b32_e32 v51, v2
	v_mov_b32_e32 v52, v2
	v_mov_b32_e32 v53, v2
	v_mov_b32_e32 v58, v2
	v_mov_b32_e32 v59, v2
	v_mov_b32_e32 v60, v2
	v_mov_b32_e32 v61, v2
	v_mov_b32_e32 v62, v2
	v_mov_b32_e32 v63, v2
	v_mov_b32_e32 v64, v2
	v_mov_b32_e32 v65, v2
	v_mov_b32_e32 v66, v2
	v_mov_b32_e32 v67, v2
	v_mov_b32_e32 v68, v2
	v_mov_b32_e32 v69, v2
	v_mov_b32_e32 v70, v2
	v_mov_b32_e32 v71, v2
	v_mov_b32_e32 v72, v2
	v_mov_b32_e32 v73, v2
	v_mov_b32_e32 v78, v2
	v_mov_b32_e32 v79, v2
	v_mov_b32_e32 v80, v2
	v_mov_b32_e32 v81, v2
	v_mov_b32_e32 v86, v2
	v_mov_b32_e32 v87, v2
	v_mov_b32_e32 v88, v2
	v_mov_b32_e32 v89, v2
	v_mov_b32_e32 v94, v2
	v_mov_b32_e32 v95, v2
	v_mov_b32_e32 v96, v2
	v_mov_b32_e32 v97, v2
	v_mov_b32_e32 v102, v2
	v_mov_b32_e32 v103, v2
	v_mov_b32_e32 v104, v2
	v_mov_b32_e32 v105, v2
	v_mov_b32_e32 v110, v2
	v_mov_b32_e32 v111, v2
	v_mov_b32_e32 v112, v2
	v_mov_b32_e32 v113, v2
	v_mov_b32_e32 v118, v2
	v_mov_b32_e32 v119, v2
	v_mov_b32_e32 v120, v2
	v_mov_b32_e32 v121, v2
	v_mov_b32_e32 v74, v2
	v_mov_b32_e32 v75, v2
	v_mov_b32_e32 v76, v2
	v_mov_b32_e32 v77, v2
	v_mov_b32_e32 v82, v2
	v_mov_b32_e32 v83, v2
	v_mov_b32_e32 v84, v2
	v_mov_b32_e32 v85, v2
	v_mov_b32_e32 v90, v2
	v_mov_b32_e32 v91, v2
	v_mov_b32_e32 v92, v2
	v_mov_b32_e32 v93, v2
	v_mov_b32_e32 v98, v2
	v_mov_b32_e32 v99, v2
	v_mov_b32_e32 v100, v2
	v_mov_b32_e32 v101, v2
	v_mov_b32_e32 v106, v2
	v_mov_b32_e32 v107, v2
	v_mov_b32_e32 v108, v2
	v_mov_b32_e32 v109, v2
	v_mov_b32_e32 v114, v2
	v_mov_b32_e32 v115, v2
	v_mov_b32_e32 v116, v2
	v_mov_b32_e32 v117, v2
	v_mov_b32_e32 v122, v2
	v_mov_b32_e32 v123, v2
	v_mov_b32_e32 v124, v2
	v_mov_b32_e32 v125, v2
	v_mov_b32_e32 v126, v2
	v_mov_b32_e32 v127, v2
	v_mov_b32_e32 v128, v2
	v_mov_b32_e32 v129, v2
	s_cmp_lg_u32 s18, 0
	s_cbranch_scc1 .Lsp1
	s_setprio 1
.Lsp1:
.LBB0_1013:
	s_add_i32 s78, s10, 2
	s_cmp_eq_u32 s71, s10
	s_cselect_b32 s46, s4, s28
	s_cselect_b32 s47, s5, s29
	s_cselect_b32 s44, s42, s76
	s_cselect_b32 s45, s43, s77
	s_add_u32 s10, s46, 0x80
	s_addc_u32 s11, s47, 0
	s_add_i32 s79, 0, 0x10000
	s_add_i32 s82, 0, 0x14000
	v_add_u32_e32 v142, s79, v179
	v_add_u32_e32 v160, s82, v179
	ds_read_b128 v[130:133], v142
	ds_read_b128 v[134:137], v142 offset:1024
	ds_read_b128 v[138:141], v142 offset:2048
	ds_read_b128 v[142:145], v142 offset:3072
	ds_read_b128 v[146:149], v160
	ds_read_b128 v[150:153], v160 offset:1024
	ds_read_b128 v[154:157], v160 offset:2048
	ds_read_b128 v[160:163], v160 offset:3072
	s_add_u32 s80, s28, 0x7ff80
	v_add_u32_e32 v240, 0, v178
	s_addc_u32 s81, s29, 0
	ds_read_b128 v[164:167], v240
	ds_read_b128 v[168:171], v240 offset:1024
	ds_read_b128 v[172:175], v240 offset:2048
	ds_read_b128 v[212:215], v240 offset:3072
	ds_read_b128 v[216:219], v240 offset:4096
	ds_read_b128 v[220:223], v240 offset:5120
	ds_read_b128 v[224:227], v240 offset:6144
	ds_read_b128 v[236:239], v240 offset:7168
	s_add_i32 m0, s49, 0xc000
	v_lshl_add_u64 v[176:177], s[80:81], 0, v[158:159]
	s_add_u32 s80, s80, 0x40000
	s_addc_u32 s81, s81, 0
	global_load_lds_dwordx4 v[176:177], off
	s_add_i32 m0, s49, 0xe000
	v_lshl_add_u64 v[176:177], s[80:81], 0, v[158:159]
	global_load_lds_dwordx4 v[176:177], off
	s_waitcnt vmcnt(8)
	s_waitcnt lgkmcnt(0)
	s_barrier
	s_waitcnt lgkmcnt(0)
	v_mfma_f32_16x16x32_bf16 v[126:129], v[130:133], v[164:167], v[126:129]
	v_mfma_f32_16x16x32_bf16 v[122:125], v[138:141], v[164:167], v[122:125]
	v_mfma_f32_16x16x32_bf16 v[114:117], v[130:133], v[172:175], v[114:117]
	v_mfma_f32_16x16x32_bf16 v[106:109], v[138:141], v[172:175], v[106:109]
	v_mfma_f32_16x16x32_bf16 v[98:101], v[130:133], v[216:219], v[98:101]
	v_mfma_f32_16x16x32_bf16 v[90:93], v[138:141], v[216:219], v[90:93]
	v_mfma_f32_16x16x32_bf16 v[82:85], v[130:133], v[224:227], v[82:85]
	v_mfma_f32_16x16x32_bf16 v[74:77], v[138:141], v[224:227], v[74:77]
	v_mfma_f32_16x16x32_bf16 v[126:129], v[134:137], v[168:171], v[126:129]
	v_mfma_f32_16x16x32_bf16 v[122:125], v[142:145], v[168:171], v[122:125]
	v_mfma_f32_16x16x32_bf16 v[114:117], v[134:137], v[212:215], v[114:117]
	v_mfma_f32_16x16x32_bf16 v[106:109], v[142:145], v[212:215], v[106:109]
	v_mfma_f32_16x16x32_bf16 v[98:101], v[134:137], v[220:223], v[98:101]
	v_mfma_f32_16x16x32_bf16 v[90:93], v[142:145], v[220:223], v[90:93]
	v_mfma_f32_16x16x32_bf16 v[82:85], v[134:137], v[236:239], v[82:85]
	v_mfma_f32_16x16x32_bf16 v[74:77], v[142:145], v[236:239], v[74:77]
	v_mfma_f32_16x16x32_bf16 v[118:121], v[146:149], v[164:167], v[118:121]
	v_mfma_f32_16x16x32_bf16 v[110:113], v[154:157], v[164:167], v[110:113]
	v_mfma_f32_16x16x32_bf16 v[102:105], v[146:149], v[172:175], v[102:105]
	v_mfma_f32_16x16x32_bf16 v[94:97], v[154:157], v[172:175], v[94:97]
	v_mfma_f32_16x16x32_bf16 v[86:89], v[146:149], v[216:219], v[86:89]
	v_mfma_f32_16x16x32_bf16 v[78:81], v[154:157], v[216:219], v[78:81]
	v_mfma_f32_16x16x32_bf16 v[70:73], v[146:149], v[224:227], v[70:73]
	v_mfma_f32_16x16x32_bf16 v[66:69], v[154:157], v[224:227], v[66:69]
	v_mfma_f32_16x16x32_bf16 v[118:121], v[150:153], v[168:171], v[118:121]
	v_mfma_f32_16x16x32_bf16 v[110:113], v[160:163], v[168:171], v[110:113]
	v_mfma_f32_16x16x32_bf16 v[102:105], v[150:153], v[212:215], v[102:105]
	v_mfma_f32_16x16x32_bf16 v[94:97], v[160:163], v[212:215], v[94:97]
	v_mfma_f32_16x16x32_bf16 v[86:89], v[150:153], v[220:223], v[86:89]
	v_mfma_f32_16x16x32_bf16 v[78:81], v[160:163], v[220:223], v[78:81]
	v_mfma_f32_16x16x32_bf16 v[70:73], v[150:153], v[236:239], v[70:73]
	v_mfma_f32_16x16x32_bf16 v[66:69], v[160:163], v[236:239], v[66:69]
	s_barrier
	s_mov_b64 s[80:81], s[44:45]
	ds_read_b128 v[164:167], v240 offset:16384
	ds_read_b128 v[168:171], v240 offset:17408
	ds_read_b128 v[172:175], v240 offset:18432
	ds_read_b128 v[212:215], v240 offset:19456
	ds_read_b128 v[216:219], v240 offset:20480
	ds_read_b128 v[220:223], v240 offset:21504
	ds_read_b128 v[224:227], v240 offset:22528
	ds_read_b128 v[236:239], v240 offset:23552
	s_add_i32 s79, s79, s48
	v_lshl_add_u64 v[176:177], s[80:81], 0, v[202:203]
	s_add_u32 s80, s80, 0x30000
	s_mov_b32 m0, s79
	s_addc_u32 s81, s81, 0
	global_load_lds_dwordx4 v[176:177], off
	s_add_i32 m0, s79, 0x2000
	v_lshl_add_u64 v[176:177], s[80:81], 0, v[202:203]
	s_add_u32 s80, s44, 0x60000
	s_addc_u32 s81, s45, 0
	global_load_lds_dwordx4 v[176:177], off
	s_add_i32 s79, s82, s48
	v_lshl_add_u64 v[176:177], s[80:81], 0, v[202:203]
	s_add_u32 s80, s80, 0x30000
	s_mov_b32 m0, s79
	s_addc_u32 s81, s81, 0
	global_load_lds_dwordx4 v[176:177], off
	s_add_i32 m0, s79, 0x2000
	v_lshl_add_u64 v[176:177], s[80:81], 0, v[202:203]
	s_mov_b64 s[80:81], s[46:47]
	global_load_lds_dwordx4 v[176:177], off
	s_mov_b32 m0, s49
	v_lshl_add_u64 v[176:177], s[80:81], 0, v[158:159]
	s_add_u32 s80, s80, 0x40000
	s_addc_u32 s81, s81, 0
	global_load_lds_dwordx4 v[176:177], off
	s_mov_b32 m0, s50
	v_lshl_add_u64 v[176:177], s[80:81], 0, v[158:159]
	global_load_lds_dwordx4 v[176:177], off
	s_waitcnt vmcnt(8)
	s_waitcnt lgkmcnt(0)
	s_barrier
	s_waitcnt lgkmcnt(0)
	v_mfma_f32_16x16x32_bf16 v[62:65], v[130:133], v[164:167], v[62:65]
	v_mfma_f32_16x16x32_bf16 v[58:61], v[138:141], v[164:167], v[58:61]
	v_mfma_f32_16x16x32_bf16 v[50:53], v[130:133], v[172:175], v[50:53]
	v_mfma_f32_16x16x32_bf16 v[42:45], v[138:141], v[172:175], v[42:45]
	v_mfma_f32_16x16x32_bf16 v[34:37], v[130:133], v[216:219], v[34:37]
	v_mfma_f32_16x16x32_bf16 v[26:29], v[138:141], v[216:219], v[26:29]
	v_mfma_f32_16x16x32_bf16 v[18:21], v[130:133], v[224:227], v[18:21]
	v_mfma_f32_16x16x32_bf16 v[10:13], v[138:141], v[224:227], v[10:13]
	v_mfma_f32_16x16x32_bf16 v[62:65], v[134:137], v[168:171], v[62:65]
	v_mfma_f32_16x16x32_bf16 v[58:61], v[142:145], v[168:171], v[58:61]
	v_mfma_f32_16x16x32_bf16 v[50:53], v[134:137], v[212:215], v[50:53]
	v_mfma_f32_16x16x32_bf16 v[42:45], v[142:145], v[212:215], v[42:45]
	v_mfma_f32_16x16x32_bf16 v[34:37], v[134:137], v[220:223], v[34:37]
	v_mfma_f32_16x16x32_bf16 v[26:29], v[142:145], v[220:223], v[26:29]
	v_mfma_f32_16x16x32_bf16 v[18:21], v[134:137], v[236:239], v[18:21]
	v_mfma_f32_16x16x32_bf16 v[10:13], v[142:145], v[236:239], v[10:13]
	v_mfma_f32_16x16x32_bf16 v[54:57], v[146:149], v[164:167], v[54:57]
	v_mfma_f32_16x16x32_bf16 v[46:49], v[154:157], v[164:167], v[46:49]
	v_mfma_f32_16x16x32_bf16 v[38:41], v[146:149], v[172:175], v[38:41]
	v_mfma_f32_16x16x32_bf16 v[30:33], v[154:157], v[172:175], v[30:33]
	v_mfma_f32_16x16x32_bf16 v[22:25], v[146:149], v[216:219], v[22:25]
	v_mfma_f32_16x16x32_bf16 v[14:17], v[154:157], v[216:219], v[14:17]
	v_mfma_f32_16x16x32_bf16 v[6:9], v[146:149], v[224:227], v[6:9]
	v_mfma_f32_16x16x32_bf16 v[2:5], v[154:157], v[224:227], v[2:5]
	v_mfma_f32_16x16x32_bf16 v[54:57], v[150:153], v[168:171], v[54:57]
	v_mfma_f32_16x16x32_bf16 v[46:49], v[160:163], v[168:171], v[46:49]
	v_mfma_f32_16x16x32_bf16 v[38:41], v[150:153], v[212:215], v[38:41]
	v_mfma_f32_16x16x32_bf16 v[30:33], v[160:163], v[212:215], v[30:33]
	v_mfma_f32_16x16x32_bf16 v[22:25], v[150:153], v[220:223], v[22:25]
	v_mfma_f32_16x16x32_bf16 v[14:17], v[160:163], v[220:223], v[14:17]
	v_mfma_f32_16x16x32_bf16 v[6:9], v[150:153], v[236:239], v[6:9]
	v_mfma_f32_16x16x32_bf16 v[2:5], v[160:163], v[236:239], v[2:5]
	s_barrier
	s_add_i32 s79, 0, 0x18000
	s_add_i32 s80, 0, 0x1c000
	v_add_u32_e32 v142, s79, v179
	v_add_u32_e32 v160, s80, v179
	ds_read_b128 v[130:133], v142
	ds_read_b128 v[134:137], v142 offset:1024
	ds_read_b128 v[138:141], v142 offset:2048
	ds_read_b128 v[142:145], v142 offset:3072
	ds_read_b128 v[146:149], v160
	ds_read_b128 v[150:153], v160 offset:1024
	ds_read_b128 v[154:157], v160 offset:2048
	ds_read_b128 v[160:163], v160 offset:3072
	s_add_u32 s46, s46, 0x80000
	s_addc_u32 s47, s47, 0
	ds_read_b128 v[164:167], v240 offset:32768
	ds_read_b128 v[168:171], v240 offset:33792
	ds_read_b128 v[172:175], v240 offset:34816
	ds_read_b128 v[212:215], v240 offset:35840
	ds_read_b128 v[216:219], v240 offset:36864
	ds_read_b128 v[220:223], v240 offset:37888
	ds_read_b128 v[224:227], v240 offset:38912
	ds_read_b128 v[236:239], v240 offset:39936
	s_mov_b32 m0, s51
	v_lshl_add_u64 v[176:177], s[46:47], 0, v[158:159]
	s_add_u32 s46, s46, 0x40000
	s_addc_u32 s47, s47, 0
	global_load_lds_dwordx4 v[176:177], off
	s_mov_b32 m0, s52
	v_lshl_add_u64 v[176:177], s[46:47], 0, v[158:159]
	global_load_lds_dwordx4 v[176:177], off
	s_waitcnt vmcnt(8)
	s_waitcnt lgkmcnt(0)
	s_barrier
	s_waitcnt lgkmcnt(0)
	v_mfma_f32_16x16x32_bf16 v[126:129], v[130:133], v[164:167], v[126:129]
	v_mfma_f32_16x16x32_bf16 v[122:125], v[138:141], v[164:167], v[122:125]
	v_mfma_f32_16x16x32_bf16 v[114:117], v[130:133], v[172:175], v[114:117]
	v_mfma_f32_16x16x32_bf16 v[106:109], v[138:141], v[172:175], v[106:109]
	v_mfma_f32_16x16x32_bf16 v[98:101], v[130:133], v[216:219], v[98:101]
	v_mfma_f32_16x16x32_bf16 v[90:93], v[138:141], v[216:219], v[90:93]
	v_mfma_f32_16x16x32_bf16 v[82:85], v[130:133], v[224:227], v[82:85]
	v_mfma_f32_16x16x32_bf16 v[74:77], v[138:141], v[224:227], v[74:77]
	v_mfma_f32_16x16x32_bf16 v[126:129], v[134:137], v[168:171], v[126:129]
	v_mfma_f32_16x16x32_bf16 v[122:125], v[142:145], v[168:171], v[122:125]
	v_mfma_f32_16x16x32_bf16 v[114:117], v[134:137], v[212:215], v[114:117]
	v_mfma_f32_16x16x32_bf16 v[106:109], v[142:145], v[212:215], v[106:109]
	v_mfma_f32_16x16x32_bf16 v[98:101], v[134:137], v[220:223], v[98:101]
	v_mfma_f32_16x16x32_bf16 v[90:93], v[142:145], v[220:223], v[90:93]
	v_mfma_f32_16x16x32_bf16 v[82:85], v[134:137], v[236:239], v[82:85]
	v_mfma_f32_16x16x32_bf16 v[74:77], v[142:145], v[236:239], v[74:77]
	v_mfma_f32_16x16x32_bf16 v[118:121], v[146:149], v[164:167], v[118:121]
	v_mfma_f32_16x16x32_bf16 v[110:113], v[154:157], v[164:167], v[110:113]
	v_mfma_f32_16x16x32_bf16 v[102:105], v[146:149], v[172:175], v[102:105]
	v_mfma_f32_16x16x32_bf16 v[94:97], v[154:157], v[172:175], v[94:97]
	v_mfma_f32_16x16x32_bf16 v[86:89], v[146:149], v[216:219], v[86:89]
	v_mfma_f32_16x16x32_bf16 v[78:81], v[154:157], v[216:219], v[78:81]
	v_mfma_f32_16x16x32_bf16 v[70:73], v[146:149], v[224:227], v[70:73]
	v_mfma_f32_16x16x32_bf16 v[66:69], v[154:157], v[224:227], v[66:69]
	v_mfma_f32_16x16x32_bf16 v[118:121], v[150:153], v[168:171], v[118:121]
	v_mfma_f32_16x16x32_bf16 v[110:113], v[160:163], v[168:171], v[110:113]
	v_mfma_f32_16x16x32_bf16 v[102:105], v[150:153], v[212:215], v[102:105]
	v_mfma_f32_16x16x32_bf16 v[94:97], v[160:163], v[212:215], v[94:97]
	v_mfma_f32_16x16x32_bf16 v[86:89], v[150:153], v[220:223], v[86:89]
	v_mfma_f32_16x16x32_bf16 v[78:81], v[160:163], v[220:223], v[78:81]
	v_mfma_f32_16x16x32_bf16 v[70:73], v[150:153], v[236:239], v[70:73]
	v_mfma_f32_16x16x32_bf16 v[66:69], v[160:163], v[236:239], v[66:69]
	s_barrier
	s_add_u32 s46, s44, 0x80
	s_addc_u32 s47, s45, 0
	ds_read_b128 v[164:167], v240 offset:49152
	ds_read_b128 v[168:171], v240 offset:50176
	ds_read_b128 v[172:175], v240 offset:51200
	ds_read_b128 v[212:215], v240 offset:52224
	ds_read_b128 v[216:219], v240 offset:53248
	ds_read_b128 v[220:223], v240 offset:54272
	ds_read_b128 v[224:227], v240 offset:55296
	ds_read_b128 v[236:239], v240 offset:56320
	s_add_i32 s79, s79, s48
	v_lshl_add_u64 v[176:177], s[46:47], 0, v[202:203]
	s_mov_b32 m0, s79
	s_add_u32 s46, s46, 0x30000
	global_load_lds_dwordx4 v[176:177], off
	s_addc_u32 s47, s47, 0
	s_add_i32 m0, s79, 0x2000
	s_add_u32 s44, s44, 0x60080
	s_addc_u32 s45, s45, 0
	v_lshl_add_u64 v[176:177], s[46:47], 0, v[202:203]
	global_load_lds_dwordx4 v[176:177], off
	s_add_i32 s46, s80, s48
	v_lshl_add_u64 v[176:177], s[44:45], 0, v[202:203]
	s_add_u32 s44, s44, 0x30000
	s_mov_b32 m0, s46
	s_addc_u32 s45, s45, 0
	global_load_lds_dwordx4 v[176:177], off
	s_add_i32 m0, s46, 0x2000
	v_lshl_add_u64 v[176:177], s[44:45], 0, v[202:203]
	global_load_lds_dwordx4 v[176:177], off
	s_mov_b32 m0, s53
	v_lshl_add_u64 v[176:177], s[10:11], 0, v[158:159]
	s_add_u32 s10, s10, 0x40000
	s_addc_u32 s11, s11, 0
	global_load_lds_dwordx4 v[176:177], off
	s_mov_b32 m0, s54
	v_lshl_add_u64 v[176:177], s[10:11], 0, v[158:159]
	global_load_lds_dwordx4 v[176:177], off
	s_waitcnt vmcnt(8)
	s_waitcnt lgkmcnt(0)
	s_barrier
	s_waitcnt lgkmcnt(0)
	v_mfma_f32_16x16x32_bf16 v[62:65], v[130:133], v[164:167], v[62:65]
	v_mfma_f32_16x16x32_bf16 v[58:61], v[138:141], v[164:167], v[58:61]
	v_mfma_f32_16x16x32_bf16 v[50:53], v[130:133], v[172:175], v[50:53]
	v_mfma_f32_16x16x32_bf16 v[42:45], v[138:141], v[172:175], v[42:45]
	v_mfma_f32_16x16x32_bf16 v[34:37], v[130:133], v[216:219], v[34:37]
	v_mfma_f32_16x16x32_bf16 v[26:29], v[138:141], v[216:219], v[26:29]
	v_mfma_f32_16x16x32_bf16 v[18:21], v[130:133], v[224:227], v[18:21]
	v_mfma_f32_16x16x32_bf16 v[10:13], v[138:141], v[224:227], v[10:13]
	v_mfma_f32_16x16x32_bf16 v[62:65], v[134:137], v[168:171], v[62:65]
	v_mfma_f32_16x16x32_bf16 v[58:61], v[142:145], v[168:171], v[58:61]
	v_mfma_f32_16x16x32_bf16 v[50:53], v[134:137], v[212:215], v[50:53]
	v_mfma_f32_16x16x32_bf16 v[42:45], v[142:145], v[212:215], v[42:45]
	v_mfma_f32_16x16x32_bf16 v[34:37], v[134:137], v[220:223], v[34:37]
	v_mfma_f32_16x16x32_bf16 v[26:29], v[142:145], v[220:223], v[26:29]
	v_mfma_f32_16x16x32_bf16 v[18:21], v[134:137], v[236:239], v[18:21]
	v_mfma_f32_16x16x32_bf16 v[10:13], v[142:145], v[236:239], v[10:13]
	v_mfma_f32_16x16x32_bf16 v[54:57], v[146:149], v[164:167], v[54:57]
	v_mfma_f32_16x16x32_bf16 v[46:49], v[154:157], v[164:167], v[46:49]
	v_mfma_f32_16x16x32_bf16 v[38:41], v[146:149], v[172:175], v[38:41]
	v_mfma_f32_16x16x32_bf16 v[30:33], v[154:157], v[172:175], v[30:33]
	v_mfma_f32_16x16x32_bf16 v[22:25], v[146:149], v[216:219], v[22:25]
	v_mfma_f32_16x16x32_bf16 v[14:17], v[154:157], v[216:219], v[14:17]
	v_mfma_f32_16x16x32_bf16 v[6:9], v[146:149], v[224:227], v[6:9]
	v_mfma_f32_16x16x32_bf16 v[2:5], v[154:157], v[224:227], v[2:5]
	v_mfma_f32_16x16x32_bf16 v[54:57], v[150:153], v[168:171], v[54:57]
	v_mfma_f32_16x16x32_bf16 v[46:49], v[160:163], v[168:171], v[46:49]
	v_mfma_f32_16x16x32_bf16 v[38:41], v[150:153], v[212:215], v[38:41]
	v_mfma_f32_16x16x32_bf16 v[30:33], v[160:163], v[212:215], v[30:33]
	v_mfma_f32_16x16x32_bf16 v[22:25], v[150:153], v[220:223], v[22:25]
	v_mfma_f32_16x16x32_bf16 v[14:17], v[160:163], v[220:223], v[14:17]
	v_mfma_f32_16x16x32_bf16 v[6:9], v[150:153], v[236:239], v[6:9]
	v_mfma_f32_16x16x32_bf16 v[2:5], v[160:163], v[236:239], v[2:5]
	s_barrier
	s_add_u32 s28, s28, 0x100
	s_addc_u32 s29, s29, 0
	s_add_u32 s76, s76, 0x100
	s_addc_u32 s77, s77, 0
	s_cmp_ge_i32 s78, s69
	s_mov_b32 s10, s78
	s_cbranch_scc0 .LBB0_1013
	s_setprio 0
	s_and_b64 vcc, exec, s[18:19]
	s_cbranch_vccz .LBB0_1016
	s_barrier

.LBB0_1025:
	s_mov_b32 s10, 0
	v_mov_b32_e32 v2, 0
	v_mov_b32_e32 v3, 0
	v_mov_b32_e32 v4, 0
	v_mov_b32_e32 v5, 0
	v_mov_b32_e32 v6, 0
	v_mov_b32_e32 v7, 0
	v_mov_b32_e32 v8, 0
	v_mov_b32_e32 v9, 0
	s_waitcnt vmcnt(0)
	v_mov_b32_e32 v18, 0
	v_mov_b32_e32 v19, 0
	v_mov_b32_e32 v20, 0
	v_mov_b32_e32 v21, 0
	v_mov_b32_e32 v22, 0
	v_mov_b32_e32 v23, 0
	v_mov_b32_e32 v24, 0
	v_mov_b32_e32 v25, 0
	v_mov_b32_e32 v26, 0
	v_mov_b32_e32 v27, 0
	v_mov_b32_e32 v28, 0
	v_mov_b32_e32 v29, 0
	v_mov_b32_e32 v30, 0
	v_mov_b32_e32 v31, 0
	v_mov_b32_e32 v32, 0
	v_mov_b32_e32 v33, 0
	v_mov_b32_e32 v42, 0
	v_mov_b32_e32 v43, 0
	v_mov_b32_e32 v44, 0
	v_mov_b32_e32 v45, 0
	v_mov_b32_e32 v46, 0
	v_mov_b32_e32 v47, 0
	v_mov_b32_e32 v48, 0
	v_mov_b32_e32 v49, 0
	v_mov_b32_e32 v10, 0
	v_mov_b32_e32 v11, 0
	v_mov_b32_e32 v12, 0
	v_mov_b32_e32 v13, 0
	v_mov_b32_e32 v14, 0
	v_mov_b32_e32 v15, 0
	v_mov_b32_e32 v16, 0
	v_mov_b32_e32 v17, 0
	v_mov_b32_e32 v34, 0
	v_mov_b32_e32 v35, 0
	v_mov_b32_e32 v36, 0
	v_mov_b32_e32 v37, 0
	v_mov_b32_e32 v38, 0
	v_mov_b32_e32 v39, 0
	v_mov_b32_e32 v40, 0
	v_mov_b32_e32 v41, 0
	v_mov_b32_e32 v50, 0
	v_mov_b32_e32 v51, 0
	v_mov_b32_e32 v52, 0
	v_mov_b32_e32 v53, 0
	v_mov_b32_e32 v54, 0
	v_mov_b32_e32 v55, 0
	v_mov_b32_e32 v56, 0
	v_mov_b32_e32 v57, 0
	v_mov_b32_e32 v58, 0
	v_mov_b32_e32 v59, 0
	v_mov_b32_e32 v60, 0
	v_mov_b32_e32 v61, 0
	v_mov_b32_e32 v62, 0
	v_mov_b32_e32 v63, 0
	v_mov_b32_e32 v64, 0
	v_mov_b32_e32 v65, 0
	v_mov_b32_e32 v66, 0
	v_mov_b32_e32 v67, 0
	v_mov_b32_e32 v68, 0
	v_mov_b32_e32 v69, 0
	v_mov_b32_e32 v70, 0
	v_mov_b32_e32 v71, 0
	v_mov_b32_e32 v72, 0
	v_mov_b32_e32 v73, 0
	v_mov_b32_e32 v74, 0
	v_mov_b32_e32 v75, 0
	v_mov_b32_e32 v76, 0
	v_mov_b32_e32 v77, 0
	v_mov_b32_e32 v78, 0
	v_mov_b32_e32 v79, 0
	v_mov_b32_e32 v80, 0
	v_mov_b32_e32 v81, 0
	v_mov_b32_e32 v90, 0
	v_mov_b32_e32 v91, 0
	v_mov_b32_e32 v92, 0
	v_mov_b32_e32 v93, 0
	v_mov_b32_e32 v94, 0
	v_mov_b32_e32 v95, 0
	v_mov_b32_e32 v96, 0
	v_mov_b32_e32 v97, 0
	v_mov_b32_e32 v106, 0
	v_mov_b32_e32 v107, 0
	v_mov_b32_e32 v108, 0
	v_mov_b32_e32 v109, 0
	v_mov_b32_e32 v110, 0
	v_mov_b32_e32 v111, 0
	v_mov_b32_e32 v112, 0
	v_mov_b32_e32 v113, 0
	v_mov_b32_e32 v82, 0
	v_mov_b32_e32 v83, 0
	v_mov_b32_e32 v84, 0
	v_mov_b32_e32 v85, 0
	v_mov_b32_e32 v86, 0
	v_mov_b32_e32 v87, 0
	v_mov_b32_e32 v88, 0
	v_mov_b32_e32 v89, 0
	v_mov_b32_e32 v98, 0
	v_mov_b32_e32 v99, 0
	v_mov_b32_e32 v100, 0
	v_mov_b32_e32 v101, 0
	v_mov_b32_e32 v102, 0
	v_mov_b32_e32 v103, 0
	v_mov_b32_e32 v104, 0
	v_mov_b32_e32 v105, 0
	v_mov_b32_e32 v114, 0
	v_mov_b32_e32 v115, 0
	v_mov_b32_e32 v116, 0
	v_mov_b32_e32 v117, 0
	v_mov_b32_e32 v118, 0
	v_mov_b32_e32 v119, 0
	v_mov_b32_e32 v120, 0
	v_mov_b32_e32 v121, 0
	v_mov_b32_e32 v122, 0
	v_mov_b32_e32 v123, 0
	v_mov_b32_e32 v124, 0
	v_mov_b32_e32 v125, 0
	v_mov_b32_e32 v126, 0
	v_mov_b32_e32 v127, 0
	v_mov_b32_e32 v128, 0
	v_mov_b32_e32 v129, 0
	s_cmp_lg_u32 s18, 0
	s_cbranch_scc1 .Lsp2
	s_setprio 1
.Lsp2:
.LBB0_1026:
	s_add_i32 s28, s10, 2
	s_cmp_eq_u32 s71, s10
	s_cselect_b32 s46, s4, s74
	s_cselect_b32 s47, s5, s75
	s_cselect_b32 s44, s42, s72
	s_cselect_b32 s45, s43, s73
	s_cbranch_scc0 .Lg0_nopf
	v_mbcnt_lo_u32_b32 v250, -1, 0
	v_mbcnt_hi_u32_b32 v250, -1, v250
	v_lshlrev_b32_e32 v251, 4, v250
	s_lshl_b32 s76, s67, 13
	s_add_u32 s76, s20, s76
	s_addc_u32 s77, s21, 0
	v_add_u32_e32 v252, s49, v251
	s_add_i32 m0, s49, 0x24f80
	s_nop 0
	global_load_lds_dwordx4 v252, s[76:77]
	s_lshl_b32 s76, s68, 12
	s_lshl_b32 s77, s70, 10
	s_add_i32 s76, s76, s77
	s_add_u32 s76, s57, s76
	s_addc_u32 s77, s60, 0
	s_mov_b32 m0, 0x26f80
	s_nop 0
	global_load_lds_dwordx4 v251, s[76:77]
	s_lshl_b32 s76, s67, 10
	s_add_u32 s76, s22, s76
	s_addc_u32 s77, s23, 0
	s_mov_b32 m0, 0x27380
	s_nop 0
	global_load_lds_dwordx4 v251, s[76:77]
	s_ashr_i32 s76, s68, 1
	s_lshl_b32 s76, s76, 2
	s_add_u32 s76, s12, s76
	s_addc_u32 s77, s61, 0
	v_mov_b32_e32 v253, 0
	s_mov_b32 m0, 0x27780
	s_nop 0
	global_load_lds_dword v253, s[76:77] sc1
.Lg0_nopf:
	s_add_u32 s10, s46, 0x80
	s_addc_u32 s11, s47, 0
	s_add_i32 s29, 0, 0x10000
	s_add_i32 s78, 0, 0x14000
	v_add_u32_e32 v142, s29, v179
	v_add_u32_e32 v160, s78, v179
	ds_read_b128 v[130:133], v142
	ds_read_b128 v[134:137], v142 offset:1024
	ds_read_b128 v[138:141], v142 offset:2048
	ds_read_b128 v[142:145], v142 offset:3072
	ds_read_b128 v[146:149], v160
	ds_read_b128 v[150:153], v160 offset:1024
	ds_read_b128 v[154:157], v160 offset:2048
	ds_read_b128 v[160:163], v160 offset:3072
	s_add_u32 s76, s74, 0x7ff80
	v_add_u32_e32 v200, 0, v178
	s_addc_u32 s77, s75, 0
	ds_read_b128 v[164:167], v200
	ds_read_b128 v[168:171], v200 offset:1024
	ds_read_b128 v[172:175], v200 offset:2048
	ds_read_b128 v[180:183], v200 offset:3072
	ds_read_b128 v[184:187], v200 offset:4096
	ds_read_b128 v[188:191], v200 offset:5120
	ds_read_b128 v[192:195], v200 offset:6144
	ds_read_b128 v[196:199], v200 offset:7168
	s_add_i32 m0, s49, 0xc000
	v_lshl_add_u64 v[176:177], s[76:77], 0, v[158:159]
	s_add_u32 s76, s76, 0x40000
	s_addc_u32 s77, s77, 0
	global_load_lds_dwordx4 v[176:177], off
	s_add_i32 m0, s49, 0xe000
	v_lshl_add_u64 v[176:177], s[76:77], 0, v[158:159]
	global_load_lds_dwordx4 v[176:177], off
	s_waitcnt vmcnt(8)
	s_waitcnt lgkmcnt(0)
	s_barrier
	s_waitcnt lgkmcnt(0)
	v_mfma_i32_16x16x64_i8 v[126:129], v[130:133], v[164:167], v[126:129]
	v_mfma_i32_16x16x64_i8 v[122:125], v[138:141], v[164:167], v[122:125]
	v_mfma_i32_16x16x64_i8 v[118:121], v[130:133], v[172:175], v[118:121]
	v_mfma_i32_16x16x64_i8 v[114:117], v[138:141], v[172:175], v[114:117]
	v_mfma_i32_16x16x64_i8 v[102:105], v[130:133], v[184:187], v[102:105]
	v_mfma_i32_16x16x64_i8 v[98:101], v[138:141], v[184:187], v[98:101]
	v_mfma_i32_16x16x64_i8 v[86:89], v[130:133], v[192:195], v[86:89]
	v_mfma_i32_16x16x64_i8 v[82:85], v[138:141], v[192:195], v[82:85]
	v_mfma_i32_16x16x64_i8 v[126:129], v[134:137], v[168:171], v[126:129]
	v_mfma_i32_16x16x64_i8 v[122:125], v[142:145], v[168:171], v[122:125]
	v_mfma_i32_16x16x64_i8 v[118:121], v[134:137], v[180:183], v[118:121]
	v_mfma_i32_16x16x64_i8 v[114:117], v[142:145], v[180:183], v[114:117]
	v_mfma_i32_16x16x64_i8 v[102:105], v[134:137], v[188:191], v[102:105]
	v_mfma_i32_16x16x64_i8 v[98:101], v[142:145], v[188:191], v[98:101]
	v_mfma_i32_16x16x64_i8 v[86:89], v[134:137], v[196:199], v[86:89]
	v_mfma_i32_16x16x64_i8 v[82:85], v[142:145], v[196:199], v[82:85]
	v_mfma_i32_16x16x64_i8 v[110:113], v[146:149], v[164:167], v[110:113]
	v_mfma_i32_16x16x64_i8 v[106:109], v[154:157], v[164:167], v[106:109]
	v_mfma_i32_16x16x64_i8 v[94:97], v[146:149], v[172:175], v[94:97]
	v_mfma_i32_16x16x64_i8 v[90:93], v[154:157], v[172:175], v[90:93]
	v_mfma_i32_16x16x64_i8 v[78:81], v[146:149], v[184:187], v[78:81]
	v_mfma_i32_16x16x64_i8 v[74:77], v[154:157], v[184:187], v[74:77]
	v_mfma_i32_16x16x64_i8 v[70:73], v[146:149], v[192:195], v[70:73]
	v_mfma_i32_16x16x64_i8 v[66:69], v[154:157], v[192:195], v[66:69]
	v_mfma_i32_16x16x64_i8 v[110:113], v[150:153], v[168:171], v[110:113]
	v_mfma_i32_16x16x64_i8 v[106:109], v[160:163], v[168:171], v[106:109]
	v_mfma_i32_16x16x64_i8 v[94:97], v[150:153], v[180:183], v[94:97]
	v_mfma_i32_16x16x64_i8 v[90:93], v[160:163], v[180:183], v[90:93]
	v_mfma_i32_16x16x64_i8 v[78:81], v[150:153], v[188:191], v[78:81]
	v_mfma_i32_16x16x64_i8 v[74:77], v[160:163], v[188:191], v[74:77]
	v_mfma_i32_16x16x64_i8 v[70:73], v[150:153], v[196:199], v[70:73]
	v_mfma_i32_16x16x64_i8 v[66:69], v[160:163], v[196:199], v[66:69]
	s_barrier
	s_mov_b64 s[76:77], s[44:45]
	ds_read_b128 v[164:167], v200 offset:16384
	ds_read_b128 v[168:171], v200 offset:17408
	ds_read_b128 v[172:175], v200 offset:18432
	ds_read_b128 v[180:183], v200 offset:19456
	ds_read_b128 v[184:187], v200 offset:20480
	ds_read_b128 v[188:191], v200 offset:21504
	ds_read_b128 v[192:195], v200 offset:22528
	ds_read_b128 v[196:199], v200 offset:23552
	s_add_i32 s29, s29, s48
	v_lshl_add_u64 v[176:177], s[76:77], 0, v[202:203]
	s_add_u32 s76, s76, 0x30000
	s_mov_b32 m0, s29
	s_addc_u32 s77, s77, 0
	global_load_lds_dwordx4 v[176:177], off
	s_add_i32 m0, s29, 0x2000
	v_lshl_add_u64 v[176:177], s[76:77], 0, v[202:203]
	s_add_u32 s76, s44, 0x60000
	s_addc_u32 s77, s45, 0
	global_load_lds_dwordx4 v[176:177], off
	s_add_i32 s29, s78, s48
	v_lshl_add_u64 v[176:177], s[76:77], 0, v[202:203]
	s_add_u32 s76, s76, 0x30000
	s_mov_b32 m0, s29
	s_addc_u32 s77, s77, 0
	global_load_lds_dwordx4 v[176:177], off
	s_add_i32 m0, s29, 0x2000
	v_lshl_add_u64 v[176:177], s[76:77], 0, v[202:203]
	s_mov_b64 s[76:77], s[46:47]
	global_load_lds_dwordx4 v[176:177], off
	s_mov_b32 m0, s49
	v_lshl_add_u64 v[176:177], s[76:77], 0, v[158:159]
	s_add_u32 s76, s76, 0x40000
	s_addc_u32 s77, s77, 0
	global_load_lds_dwordx4 v[176:177], off
	s_mov_b32 m0, s50
	v_lshl_add_u64 v[176:177], s[76:77], 0, v[158:159]
	global_load_lds_dwordx4 v[176:177], off
	s_waitcnt vmcnt(8)
	s_waitcnt lgkmcnt(0)
	s_barrier
	s_waitcnt lgkmcnt(0)
	v_mfma_i32_16x16x64_i8 v[62:65], v[130:133], v[164:167], v[62:65]
	v_mfma_i32_16x16x64_i8 v[58:61], v[138:141], v[164:167], v[58:61]
	v_mfma_i32_16x16x64_i8 v[54:57], v[130:133], v[172:175], v[54:57]
	v_mfma_i32_16x16x64_i8 v[50:53], v[138:141], v[172:175], v[50:53]
	v_mfma_i32_16x16x64_i8 v[38:41], v[130:133], v[184:187], v[38:41]
	v_mfma_i32_16x16x64_i8 v[34:37], v[138:141], v[184:187], v[34:37]
	v_mfma_i32_16x16x64_i8 v[14:17], v[130:133], v[192:195], v[14:17]
	v_mfma_i32_16x16x64_i8 v[10:13], v[138:141], v[192:195], v[10:13]
	v_mfma_i32_16x16x64_i8 v[62:65], v[134:137], v[168:171], v[62:65]
	v_mfma_i32_16x16x64_i8 v[58:61], v[142:145], v[168:171], v[58:61]
	v_mfma_i32_16x16x64_i8 v[54:57], v[134:137], v[180:183], v[54:57]
	v_mfma_i32_16x16x64_i8 v[50:53], v[142:145], v[180:183], v[50:53]
	v_mfma_i32_16x16x64_i8 v[38:41], v[134:137], v[188:191], v[38:41]
	v_mfma_i32_16x16x64_i8 v[34:37], v[142:145], v[188:191], v[34:37]
	v_mfma_i32_16x16x64_i8 v[14:17], v[134:137], v[196:199], v[14:17]
	v_mfma_i32_16x16x64_i8 v[10:13], v[142:145], v[196:199], v[10:13]
	v_mfma_i32_16x16x64_i8 v[46:49], v[146:149], v[164:167], v[46:49]
	v_mfma_i32_16x16x64_i8 v[42:45], v[154:157], v[164:167], v[42:45]
	v_mfma_i32_16x16x64_i8 v[30:33], v[146:149], v[172:175], v[30:33]
	v_mfma_i32_16x16x64_i8 v[26:29], v[154:157], v[172:175], v[26:29]
	v_mfma_i32_16x16x64_i8 v[22:25], v[146:149], v[184:187], v[22:25]
	v_mfma_i32_16x16x64_i8 v[18:21], v[154:157], v[184:187], v[18:21]
	v_mfma_i32_16x16x64_i8 v[6:9], v[146:149], v[192:195], v[6:9]
	v_mfma_i32_16x16x64_i8 v[2:5], v[154:157], v[192:195], v[2:5]
	v_mfma_i32_16x16x64_i8 v[46:49], v[150:153], v[168:171], v[46:49]
	v_mfma_i32_16x16x64_i8 v[42:45], v[160:163], v[168:171], v[42:45]
	v_mfma_i32_16x16x64_i8 v[30:33], v[150:153], v[180:183], v[30:33]
	v_mfma_i32_16x16x64_i8 v[26:29], v[160:163], v[180:183], v[26:29]
	v_mfma_i32_16x16x64_i8 v[22:25], v[150:153], v[188:191], v[22:25]
	v_mfma_i32_16x16x64_i8 v[18:21], v[160:163], v[188:191], v[18:21]
	v_mfma_i32_16x16x64_i8 v[6:9], v[150:153], v[196:199], v[6:9]
	v_mfma_i32_16x16x64_i8 v[2:5], v[160:163], v[196:199], v[2:5]
	s_barrier
	s_add_i32 s29, 0, 0x18000
	s_add_i32 s76, 0, 0x1c000
	v_add_u32_e32 v142, s29, v179
	v_add_u32_e32 v160, s76, v179
	ds_read_b128 v[130:133], v142
	ds_read_b128 v[134:137], v142 offset:1024
	ds_read_b128 v[138:141], v142 offset:2048
	ds_read_b128 v[142:145], v142 offset:3072
	ds_read_b128 v[146:149], v160
	ds_read_b128 v[150:153], v160 offset:1024
	ds_read_b128 v[154:157], v160 offset:2048
	ds_read_b128 v[160:163], v160 offset:3072
	s_add_u32 s46, s46, 0x80000
	s_addc_u32 s47, s47, 0
	ds_read_b128 v[164:167], v200 offset:32768
	ds_read_b128 v[168:171], v200 offset:33792
	ds_read_b128 v[172:175], v200 offset:34816
	ds_read_b128 v[180:183], v200 offset:35840
	ds_read_b128 v[184:187], v200 offset:36864
	ds_read_b128 v[188:191], v200 offset:37888
	ds_read_b128 v[192:195], v200 offset:38912
	ds_read_b128 v[196:199], v200 offset:39936
	s_mov_b32 m0, s51
	v_lshl_add_u64 v[176:177], s[46:47], 0, v[158:159]
	s_add_u32 s46, s46, 0x40000
	s_addc_u32 s47, s47, 0
	global_load_lds_dwordx4 v[176:177], off
	s_mov_b32 m0, s52
	v_lshl_add_u64 v[176:177], s[46:47], 0, v[158:159]
	global_load_lds_dwordx4 v[176:177], off
	s_waitcnt vmcnt(8)
	s_waitcnt lgkmcnt(0)
	s_barrier
	s_waitcnt lgkmcnt(0)
	v_mfma_i32_16x16x64_i8 v[126:129], v[130:133], v[164:167], v[126:129]
	v_mfma_i32_16x16x64_i8 v[122:125], v[138:141], v[164:167], v[122:125]
	v_mfma_i32_16x16x64_i8 v[118:121], v[130:133], v[172:175], v[118:121]
	v_mfma_i32_16x16x64_i8 v[114:117], v[138:141], v[172:175], v[114:117]
	v_mfma_i32_16x16x64_i8 v[102:105], v[130:133], v[184:187], v[102:105]
	v_mfma_i32_16x16x64_i8 v[98:101], v[138:141], v[184:187], v[98:101]
	v_mfma_i32_16x16x64_i8 v[86:89], v[130:133], v[192:195], v[86:89]
	v_mfma_i32_16x16x64_i8 v[82:85], v[138:141], v[192:195], v[82:85]
	v_mfma_i32_16x16x64_i8 v[126:129], v[134:137], v[168:171], v[126:129]
	v_mfma_i32_16x16x64_i8 v[122:125], v[142:145], v[168:171], v[122:125]
	v_mfma_i32_16x16x64_i8 v[118:121], v[134:137], v[180:183], v[118:121]
	v_mfma_i32_16x16x64_i8 v[114:117], v[142:145], v[180:183], v[114:117]
	v_mfma_i32_16x16x64_i8 v[102:105], v[134:137], v[188:191], v[102:105]
	v_mfma_i32_16x16x64_i8 v[98:101], v[142:145], v[188:191], v[98:101]
	v_mfma_i32_16x16x64_i8 v[86:89], v[134:137], v[196:199], v[86:89]
	v_mfma_i32_16x16x64_i8 v[82:85], v[142:145], v[196:199], v[82:85]
	v_mfma_i32_16x16x64_i8 v[110:113], v[146:149], v[164:167], v[110:113]
	v_mfma_i32_16x16x64_i8 v[106:109], v[154:157], v[164:167], v[106:109]
	v_mfma_i32_16x16x64_i8 v[94:97], v[146:149], v[172:175], v[94:97]
	v_mfma_i32_16x16x64_i8 v[90:93], v[154:157], v[172:175], v[90:93]
	v_mfma_i32_16x16x64_i8 v[78:81], v[146:149], v[184:187], v[78:81]
	v_mfma_i32_16x16x64_i8 v[74:77], v[154:157], v[184:187], v[74:77]
	v_mfma_i32_16x16x64_i8 v[70:73], v[146:149], v[192:195], v[70:73]
	v_mfma_i32_16x16x64_i8 v[66:69], v[154:157], v[192:195], v[66:69]
	v_mfma_i32_16x16x64_i8 v[110:113], v[150:153], v[168:171], v[110:113]
	v_mfma_i32_16x16x64_i8 v[106:109], v[160:163], v[168:171], v[106:109]
	v_mfma_i32_16x16x64_i8 v[94:97], v[150:153], v[180:183], v[94:97]
	v_mfma_i32_16x16x64_i8 v[90:93], v[160:163], v[180:183], v[90:93]
	v_mfma_i32_16x16x64_i8 v[78:81], v[150:153], v[188:191], v[78:81]
	v_mfma_i32_16x16x64_i8 v[74:77], v[160:163], v[188:191], v[74:77]
	v_mfma_i32_16x16x64_i8 v[70:73], v[150:153], v[196:199], v[70:73]
	v_mfma_i32_16x16x64_i8 v[66:69], v[160:163], v[196:199], v[66:69]
	s_barrier
	s_add_u32 s46, s44, 0x80
	s_addc_u32 s47, s45, 0
	ds_read_b128 v[164:167], v200 offset:49152
	ds_read_b128 v[168:171], v200 offset:50176
	ds_read_b128 v[172:175], v200 offset:51200
	ds_read_b128 v[180:183], v200 offset:52224
	ds_read_b128 v[184:187], v200 offset:53248
	ds_read_b128 v[188:191], v200 offset:54272
	ds_read_b128 v[192:195], v200 offset:55296
	ds_read_b128 v[196:199], v200 offset:56320
	s_add_i32 s29, s29, s48
	v_lshl_add_u64 v[176:177], s[46:47], 0, v[202:203]
	s_mov_b32 m0, s29
	s_add_u32 s46, s46, 0x30000
	global_load_lds_dwordx4 v[176:177], off
	s_addc_u32 s47, s47, 0
	s_add_i32 m0, s29, 0x2000
	s_add_u32 s44, s44, 0x60080
	s_addc_u32 s45, s45, 0
	v_lshl_add_u64 v[176:177], s[46:47], 0, v[202:203]
	global_load_lds_dwordx4 v[176:177], off
	s_add_i32 s29, s76, s48
	v_lshl_add_u64 v[176:177], s[44:45], 0, v[202:203]
	s_add_u32 s44, s44, 0x30000
	s_mov_b32 m0, s29
	s_addc_u32 s45, s45, 0
	global_load_lds_dwordx4 v[176:177], off
	s_add_i32 m0, s29, 0x2000
	v_lshl_add_u64 v[176:177], s[44:45], 0, v[202:203]
	global_load_lds_dwordx4 v[176:177], off
	s_mov_b32 m0, s53
	v_lshl_add_u64 v[176:177], s[10:11], 0, v[158:159]
	s_add_u32 s10, s10, 0x40000
	s_addc_u32 s11, s11, 0
	global_load_lds_dwordx4 v[176:177], off
	s_mov_b32 m0, s54
	v_lshl_add_u64 v[176:177], s[10:11], 0, v[158:159]
	global_load_lds_dwordx4 v[176:177], off
	s_waitcnt vmcnt(8)
	s_waitcnt lgkmcnt(0)
	s_barrier
	s_waitcnt lgkmcnt(0)
	v_mfma_i32_16x16x64_i8 v[62:65], v[130:133], v[164:167], v[62:65]
	v_mfma_i32_16x16x64_i8 v[58:61], v[138:141], v[164:167], v[58:61]
	v_mfma_i32_16x16x64_i8 v[54:57], v[130:133], v[172:175], v[54:57]
	v_mfma_i32_16x16x64_i8 v[50:53], v[138:141], v[172:175], v[50:53]
	v_mfma_i32_16x16x64_i8 v[38:41], v[130:133], v[184:187], v[38:41]
	v_mfma_i32_16x16x64_i8 v[34:37], v[138:141], v[184:187], v[34:37]
	v_mfma_i32_16x16x64_i8 v[14:17], v[130:133], v[192:195], v[14:17]
	v_mfma_i32_16x16x64_i8 v[10:13], v[138:141], v[192:195], v[10:13]
	v_mfma_i32_16x16x64_i8 v[62:65], v[134:137], v[168:171], v[62:65]
	v_mfma_i32_16x16x64_i8 v[58:61], v[142:145], v[168:171], v[58:61]
	v_mfma_i32_16x16x64_i8 v[54:57], v[134:137], v[180:183], v[54:57]
	v_mfma_i32_16x16x64_i8 v[50:53], v[142:145], v[180:183], v[50:53]
	v_mfma_i32_16x16x64_i8 v[38:41], v[134:137], v[188:191], v[38:41]
	v_mfma_i32_16x16x64_i8 v[34:37], v[142:145], v[188:191], v[34:37]
	v_mfma_i32_16x16x64_i8 v[14:17], v[134:137], v[196:199], v[14:17]
	v_mfma_i32_16x16x64_i8 v[10:13], v[142:145], v[196:199], v[10:13]
	v_mfma_i32_16x16x64_i8 v[46:49], v[146:149], v[164:167], v[46:49]
	v_mfma_i32_16x16x64_i8 v[42:45], v[154:157], v[164:167], v[42:45]
	v_mfma_i32_16x16x64_i8 v[30:33], v[146:149], v[172:175], v[30:33]
	v_mfma_i32_16x16x64_i8 v[26:29], v[154:157], v[172:175], v[26:29]
	v_mfma_i32_16x16x64_i8 v[22:25], v[146:149], v[184:187], v[22:25]
	v_mfma_i32_16x16x64_i8 v[18:21], v[154:157], v[184:187], v[18:21]
	v_mfma_i32_16x16x64_i8 v[6:9], v[146:149], v[192:195], v[6:9]
	v_mfma_i32_16x16x64_i8 v[2:5], v[154:157], v[192:195], v[2:5]
	v_mfma_i32_16x16x64_i8 v[46:49], v[150:153], v[168:171], v[46:49]
	v_mfma_i32_16x16x64_i8 v[42:45], v[160:163], v[168:171], v[42:45]
	v_mfma_i32_16x16x64_i8 v[30:33], v[150:153], v[180:183], v[30:33]
	v_mfma_i32_16x16x64_i8 v[26:29], v[160:163], v[180:183], v[26:29]
	v_mfma_i32_16x16x64_i8 v[22:25], v[150:153], v[188:191], v[22:25]
	v_mfma_i32_16x16x64_i8 v[18:21], v[160:163], v[188:191], v[18:21]
	v_mfma_i32_16x16x64_i8 v[6:9], v[150:153], v[196:199], v[6:9]
	v_mfma_i32_16x16x64_i8 v[2:5], v[160:163], v[196:199], v[2:5]
	s_barrier
	s_add_u32 s74, s74, 0x100
	s_addc_u32 s75, s75, 0
	s_add_u32 s72, s72, 0x100
	s_addc_u32 s73, s73, 0
	s_cmp_ge_i32 s28, s69
	s_mov_b32 s10, s28
	s_cbranch_scc0 .LBB0_1026
	s_setprio 0
	s_and_b64 vcc, exec, s[18:19]
	s_cbranch_vccz .LBB0_1029
	s_barrier

.LBB0_1095:
	s_add_u32 s7, s46, 0x100
	s_addc_u32 s21, s47, 0
	s_add_u32 s27, s48, 0x100
	s_addc_u32 s28, s49, 0
	s_add_u32 s46, s46, 0x80080
	s_addc_u32 s47, s47, 0
	s_mov_b32 s29, -2
	s_cmp_lg_u32 s18, 0
	s_cbranch_scc1 .Lsp3
	s_setprio 1
.Lsp3:
.LBB0_1096:
	s_cmp_eq_u32 s29, 28
	s_cselect_b32 s56, s50, s7
	s_cselect_b32 s57, s51, s21
	s_cselect_b32 s54, s52, s27
	s_cselect_b32 s55, s53, s28
	s_add_u32 s48, s56, 0x80
	s_addc_u32 s49, s57, 0
	s_add_i32 s76, 0, 0x10000
	s_add_i32 s77, 0, 0x14000
	v_add_u32_e32 v142, s76, v207
	v_add_u32_e32 v158, s77, v207
	s_waitcnt lgkmcnt(0)
	s_cmp_eq_u32 s29, 28
	s_cbranch_scc0 .Lop_nopf
	s_lshl_b32 s74, s6, 13
	s_add_u32 s74, s10, s74
	s_addc_u32 s75, s11, 0
	v_mbcnt_lo_u32_b32 v250, -1, 0
	v_mbcnt_hi_u32_b32 v250, -1, v250
	v_lshl_add_u32 v250, v250, 4, s62
	s_add_i32 m0, s62, 0x24f80
	s_nop 0
	global_load_lds_dwordx4 v250, s[74:75]
.Lop_nopf:
	ds_read_b128 v[130:133], v142
	ds_read_b128 v[134:137], v142 offset:1024
	ds_read_b128 v[138:141], v142 offset:2048
	ds_read_b128 v[142:145], v142 offset:3072
	ds_read_b128 v[146:149], v158
	ds_read_b128 v[150:153], v158 offset:1024
	ds_read_b128 v[154:157], v158 offset:2048
	ds_read_b128 v[158:161], v158 offset:3072
	s_mov_b64 s[74:75], s[46:47]
	ds_read_b128 v[162:165], v237
	ds_read_b128 v[166:169], v237 offset:1024
	ds_read_b128 v[170:173], v237 offset:2048
	ds_read_b128 v[174:177], v237 offset:3072
	ds_read_b128 v[178:181], v237 offset:4096
	ds_read_b128 v[182:185], v237 offset:5120
	ds_read_b128 v[188:191], v237 offset:6144
	ds_read_b128 v[192:195], v237 offset:7168
	s_add_i32 m0, s62, 0xc000
	v_lshl_add_u64 v[196:197], s[74:75], 0, v[186:187]
	s_add_u32 s74, s74, 0x40000
	s_addc_u32 s75, s75, 0
	global_load_lds_dwordx4 v[196:197], off
	s_add_i32 m0, s62, 0xe000
	v_lshl_add_u64 v[196:197], s[74:75], 0, v[186:187]
	global_load_lds_dwordx4 v[196:197], off
	s_waitcnt vmcnt(8)
	s_waitcnt lgkmcnt(0)
	s_barrier
	s_waitcnt lgkmcnt(0)
	v_mfma_f32_16x16x32_bf16 v[2:5], v[130:133], v[162:165], v[2:5]
	v_mfma_f32_16x16x32_bf16 v[6:9], v[138:141], v[162:165], v[6:9]
	v_mfma_f32_16x16x32_bf16 v[14:17], v[130:133], v[170:173], v[14:17]
	v_mfma_f32_16x16x32_bf16 v[22:25], v[138:141], v[170:173], v[22:25]
	v_mfma_f32_16x16x32_bf16 v[30:33], v[130:133], v[178:181], v[30:33]
	v_mfma_f32_16x16x32_bf16 v[38:41], v[138:141], v[178:181], v[38:41]
	v_mfma_f32_16x16x32_bf16 v[46:49], v[130:133], v[188:191], v[46:49]
	v_mfma_f32_16x16x32_bf16 v[54:57], v[138:141], v[188:191], v[54:57]
	v_mfma_f32_16x16x32_bf16 v[2:5], v[134:137], v[166:169], v[2:5]
	v_mfma_f32_16x16x32_bf16 v[6:9], v[142:145], v[166:169], v[6:9]
	v_mfma_f32_16x16x32_bf16 v[14:17], v[134:137], v[174:177], v[14:17]
	v_mfma_f32_16x16x32_bf16 v[22:25], v[142:145], v[174:177], v[22:25]
	v_mfma_f32_16x16x32_bf16 v[30:33], v[134:137], v[182:185], v[30:33]
	v_mfma_f32_16x16x32_bf16 v[38:41], v[142:145], v[182:185], v[38:41]
	v_mfma_f32_16x16x32_bf16 v[46:49], v[134:137], v[192:195], v[46:49]
	v_mfma_f32_16x16x32_bf16 v[54:57], v[142:145], v[192:195], v[54:57]
	v_mfma_f32_16x16x32_bf16 v[10:13], v[146:149], v[162:165], v[10:13]
	v_mfma_f32_16x16x32_bf16 v[18:21], v[154:157], v[162:165], v[18:21]
	v_mfma_f32_16x16x32_bf16 v[26:29], v[146:149], v[170:173], v[26:29]
	v_mfma_f32_16x16x32_bf16 v[34:37], v[154:157], v[170:173], v[34:37]
	v_mfma_f32_16x16x32_bf16 v[42:45], v[146:149], v[178:181], v[42:45]
	v_mfma_f32_16x16x32_bf16 v[50:53], v[154:157], v[178:181], v[50:53]
	v_mfma_f32_16x16x32_bf16 v[58:61], v[146:149], v[188:191], v[58:61]
	v_mfma_f32_16x16x32_bf16 v[62:65], v[154:157], v[188:191], v[62:65]
	v_mfma_f32_16x16x32_bf16 v[10:13], v[150:153], v[166:169], v[10:13]
	v_mfma_f32_16x16x32_bf16 v[18:21], v[158:161], v[166:169], v[18:21]
	v_mfma_f32_16x16x32_bf16 v[26:29], v[150:153], v[174:177], v[26:29]
	v_mfma_f32_16x16x32_bf16 v[34:37], v[158:161], v[174:177], v[34:37]
	v_mfma_f32_16x16x32_bf16 v[42:45], v[150:153], v[182:185], v[42:45]
	v_mfma_f32_16x16x32_bf16 v[50:53], v[158:161], v[182:185], v[50:53]
	v_mfma_f32_16x16x32_bf16 v[58:61], v[150:153], v[192:195], v[58:61]
	v_mfma_f32_16x16x32_bf16 v[62:65], v[158:161], v[192:195], v[62:65]
	s_barrier
	s_mov_b64 s[74:75], s[54:55]
	ds_read_b128 v[162:165], v237 offset:16384
	ds_read_b128 v[166:169], v237 offset:17408
	ds_read_b128 v[170:173], v237 offset:18432
	ds_read_b128 v[174:177], v237 offset:19456
	ds_read_b128 v[178:181], v237 offset:20480
	ds_read_b128 v[182:185], v237 offset:21504
	ds_read_b128 v[188:191], v237 offset:22528
	ds_read_b128 v[192:195], v237 offset:23552
	s_add_i32 s76, s76, s61
	v_lshl_add_u64 v[196:197], s[74:75], 0, v[202:203]
	s_add_u32 s74, s74, 0x40000
	s_mov_b32 m0, s76
	s_addc_u32 s75, s75, 0
	global_load_lds_dwordx4 v[196:197], off
	s_add_i32 m0, s76, 0x2000
	v_lshl_add_u64 v[196:197], s[74:75], 0, v[202:203]
	s_add_u32 s74, s54, 0x80000
	s_addc_u32 s75, s55, 0
	global_load_lds_dwordx4 v[196:197], off
	s_add_i32 s76, s77, s61
	v_lshl_add_u64 v[196:197], s[74:75], 0, v[202:203]
	s_add_u32 s74, s74, 0x40000
	s_mov_b32 m0, s76
	s_addc_u32 s75, s75, 0
	global_load_lds_dwordx4 v[196:197], off
	s_add_i32 m0, s76, 0x2000
	v_lshl_add_u64 v[196:197], s[74:75], 0, v[202:203]
	s_mov_b64 s[74:75], s[56:57]
	global_load_lds_dwordx4 v[196:197], off
	s_mov_b32 m0, s62
	v_lshl_add_u64 v[196:197], s[74:75], 0, v[186:187]
	s_add_u32 s74, s74, 0x40000
	s_addc_u32 s75, s75, 0
	global_load_lds_dwordx4 v[196:197], off
	s_mov_b32 m0, s63
	v_lshl_add_u64 v[196:197], s[74:75], 0, v[186:187]
	global_load_lds_dwordx4 v[196:197], off
	s_waitcnt vmcnt(8)
	s_waitcnt lgkmcnt(0)
	s_barrier
	s_waitcnt lgkmcnt(0)
	v_mfma_f32_16x16x32_bf16 v[66:69], v[130:133], v[162:165], v[66:69]
	v_mfma_f32_16x16x32_bf16 v[70:73], v[138:141], v[162:165], v[70:73]
	v_mfma_f32_16x16x32_bf16 v[74:77], v[130:133], v[170:173], v[74:77]
	v_mfma_f32_16x16x32_bf16 v[78:81], v[138:141], v[170:173], v[78:81]
	v_mfma_f32_16x16x32_bf16 v[86:89], v[130:133], v[178:181], v[86:89]
	v_mfma_f32_16x16x32_bf16 v[94:97], v[138:141], v[178:181], v[94:97]
	v_mfma_f32_16x16x32_bf16 v[102:105], v[130:133], v[188:191], v[102:105]
	v_mfma_f32_16x16x32_bf16 v[110:113], v[138:141], v[188:191], v[110:113]
	v_mfma_f32_16x16x32_bf16 v[66:69], v[134:137], v[166:169], v[66:69]
	v_mfma_f32_16x16x32_bf16 v[70:73], v[142:145], v[166:169], v[70:73]
	v_mfma_f32_16x16x32_bf16 v[74:77], v[134:137], v[174:177], v[74:77]
	v_mfma_f32_16x16x32_bf16 v[78:81], v[142:145], v[174:177], v[78:81]
	v_mfma_f32_16x16x32_bf16 v[86:89], v[134:137], v[182:185], v[86:89]
	v_mfma_f32_16x16x32_bf16 v[94:97], v[142:145], v[182:185], v[94:97]
	v_mfma_f32_16x16x32_bf16 v[102:105], v[134:137], v[192:195], v[102:105]
	v_mfma_f32_16x16x32_bf16 v[110:113], v[142:145], v[192:195], v[110:113]
	v_mfma_f32_16x16x32_bf16 v[82:85], v[146:149], v[162:165], v[82:85]
	v_mfma_f32_16x16x32_bf16 v[90:93], v[154:157], v[162:165], v[90:93]
	v_mfma_f32_16x16x32_bf16 v[98:101], v[146:149], v[170:173], v[98:101]
	v_mfma_f32_16x16x32_bf16 v[106:109], v[154:157], v[170:173], v[106:109]
	v_mfma_f32_16x16x32_bf16 v[114:117], v[146:149], v[178:181], v[114:117]
	v_mfma_f32_16x16x32_bf16 v[118:121], v[154:157], v[178:181], v[118:121]
	v_mfma_f32_16x16x32_bf16 v[122:125], v[146:149], v[188:191], v[122:125]
	v_mfma_f32_16x16x32_bf16 v[126:129], v[154:157], v[188:191], v[126:129]
	v_mfma_f32_16x16x32_bf16 v[82:85], v[150:153], v[166:169], v[82:85]
	v_mfma_f32_16x16x32_bf16 v[90:93], v[158:161], v[166:169], v[90:93]
	v_mfma_f32_16x16x32_bf16 v[98:101], v[150:153], v[174:177], v[98:101]
	v_mfma_f32_16x16x32_bf16 v[106:109], v[158:161], v[174:177], v[106:109]
	v_mfma_f32_16x16x32_bf16 v[114:117], v[150:153], v[182:185], v[114:117]
	v_mfma_f32_16x16x32_bf16 v[118:121], v[158:161], v[182:185], v[118:121]
	v_mfma_f32_16x16x32_bf16 v[122:125], v[150:153], v[192:195], v[122:125]
	v_mfma_f32_16x16x32_bf16 v[126:129], v[158:161], v[192:195], v[126:129]
	s_barrier
	s_add_i32 s74, 0, 0x18000
	s_add_i32 s75, 0, 0x1c000
	v_add_u32_e32 v142, s74, v207
	v_add_u32_e32 v158, s75, v207
	ds_read_b128 v[130:133], v142
	ds_read_b128 v[134:137], v142 offset:1024
	ds_read_b128 v[138:141], v142 offset:2048
	ds_read_b128 v[142:145], v142 offset:3072
	ds_read_b128 v[146:149], v158
	ds_read_b128 v[150:153], v158 offset:1024
	ds_read_b128 v[154:157], v158 offset:2048
	ds_read_b128 v[158:161], v158 offset:3072
	s_add_u32 s56, s56, 0x80000
	s_addc_u32 s57, s57, 0
	ds_read_b128 v[162:165], v237 offset:32768
	ds_read_b128 v[166:169], v237 offset:33792
	ds_read_b128 v[170:173], v237 offset:34816
	ds_read_b128 v[174:177], v237 offset:35840
	ds_read_b128 v[178:181], v237 offset:36864
	ds_read_b128 v[182:185], v237 offset:37888
	ds_read_b128 v[188:191], v237 offset:38912
	ds_read_b128 v[192:195], v237 offset:39936
	s_mov_b32 m0, s64
	v_lshl_add_u64 v[196:197], s[56:57], 0, v[186:187]
	s_add_u32 s56, s56, 0x40000
	s_addc_u32 s57, s57, 0
	global_load_lds_dwordx4 v[196:197], off
	s_mov_b32 m0, s65
	v_lshl_add_u64 v[196:197], s[56:57], 0, v[186:187]
	global_load_lds_dwordx4 v[196:197], off
	s_waitcnt vmcnt(8)
	s_waitcnt lgkmcnt(0)
	s_barrier
	s_waitcnt lgkmcnt(0)
	v_mfma_f32_16x16x32_bf16 v[2:5], v[130:133], v[162:165], v[2:5]
	v_mfma_f32_16x16x32_bf16 v[6:9], v[138:141], v[162:165], v[6:9]
	v_mfma_f32_16x16x32_bf16 v[14:17], v[130:133], v[170:173], v[14:17]
	v_mfma_f32_16x16x32_bf16 v[22:25], v[138:141], v[170:173], v[22:25]
	v_mfma_f32_16x16x32_bf16 v[30:33], v[130:133], v[178:181], v[30:33]
	v_mfma_f32_16x16x32_bf16 v[38:41], v[138:141], v[178:181], v[38:41]
	v_mfma_f32_16x16x32_bf16 v[46:49], v[130:133], v[188:191], v[46:49]
	v_mfma_f32_16x16x32_bf16 v[54:57], v[138:141], v[188:191], v[54:57]
	v_mfma_f32_16x16x32_bf16 v[2:5], v[134:137], v[166:169], v[2:5]
	v_mfma_f32_16x16x32_bf16 v[6:9], v[142:145], v[166:169], v[6:9]
	v_mfma_f32_16x16x32_bf16 v[14:17], v[134:137], v[174:177], v[14:17]
	v_mfma_f32_16x16x32_bf16 v[22:25], v[142:145], v[174:177], v[22:25]
	v_mfma_f32_16x16x32_bf16 v[30:33], v[134:137], v[182:185], v[30:33]
	v_mfma_f32_16x16x32_bf16 v[38:41], v[142:145], v[182:185], v[38:41]
	v_mfma_f32_16x16x32_bf16 v[46:49], v[134:137], v[192:195], v[46:49]
	v_mfma_f32_16x16x32_bf16 v[54:57], v[142:145], v[192:195], v[54:57]
	v_mfma_f32_16x16x32_bf16 v[10:13], v[146:149], v[162:165], v[10:13]
	v_mfma_f32_16x16x32_bf16 v[18:21], v[154:157], v[162:165], v[18:21]
	v_mfma_f32_16x16x32_bf16 v[26:29], v[146:149], v[170:173], v[26:29]
	v_mfma_f32_16x16x32_bf16 v[34:37], v[154:157], v[170:173], v[34:37]
	v_mfma_f32_16x16x32_bf16 v[42:45], v[146:149], v[178:181], v[42:45]
	v_mfma_f32_16x16x32_bf16 v[50:53], v[154:157], v[178:181], v[50:53]
	v_mfma_f32_16x16x32_bf16 v[58:61], v[146:149], v[188:191], v[58:61]
	v_mfma_f32_16x16x32_bf16 v[62:65], v[154:157], v[188:191], v[62:65]
	v_mfma_f32_16x16x32_bf16 v[10:13], v[150:153], v[166:169], v[10:13]
	v_mfma_f32_16x16x32_bf16 v[18:21], v[158:161], v[166:169], v[18:21]
	v_mfma_f32_16x16x32_bf16 v[26:29], v[150:153], v[174:177], v[26:29]
	v_mfma_f32_16x16x32_bf16 v[34:37], v[158:161], v[174:177], v[34:37]
	v_mfma_f32_16x16x32_bf16 v[42:45], v[150:153], v[182:185], v[42:45]
	v_mfma_f32_16x16x32_bf16 v[50:53], v[158:161], v[182:185], v[50:53]
	v_mfma_f32_16x16x32_bf16 v[58:61], v[150:153], v[192:195], v[58:61]
	v_mfma_f32_16x16x32_bf16 v[62:65], v[158:161], v[192:195], v[62:65]
	s_barrier
	s_add_u32 s56, s54, 0x80
	s_addc_u32 s57, s55, 0
	ds_read_b128 v[162:165], v237 offset:49152
	ds_read_b128 v[166:169], v237 offset:50176
	ds_read_b128 v[170:173], v237 offset:51200
	ds_read_b128 v[174:177], v237 offset:52224
	ds_read_b128 v[178:181], v237 offset:53248
	ds_read_b128 v[182:185], v237 offset:54272
	ds_read_b128 v[188:191], v237 offset:55296
	ds_read_b128 v[192:195], v237 offset:56320
	s_add_i32 s74, s74, s61
	v_lshl_add_u64 v[196:197], s[56:57], 0, v[202:203]
	s_mov_b32 m0, s74
	s_add_u32 s56, s56, 0x40000
	global_load_lds_dwordx4 v[196:197], off
	s_addc_u32 s57, s57, 0
	s_add_i32 m0, s74, 0x2000
	s_add_u32 s54, s54, 0x80080
	s_addc_u32 s55, s55, 0
	v_lshl_add_u64 v[196:197], s[56:57], 0, v[202:203]
	global_load_lds_dwordx4 v[196:197], off
	s_add_i32 s56, s75, s61
	v_lshl_add_u64 v[196:197], s[54:55], 0, v[202:203]
	s_add_u32 s54, s54, 0x40000
	s_mov_b32 m0, s56
	s_addc_u32 s55, s55, 0
	global_load_lds_dwordx4 v[196:197], off
	s_add_i32 m0, s56, 0x2000
	v_lshl_add_u64 v[196:197], s[54:55], 0, v[202:203]
	global_load_lds_dwordx4 v[196:197], off
	s_mov_b32 m0, s66
	v_lshl_add_u64 v[196:197], s[48:49], 0, v[186:187]
	s_add_u32 s48, s48, 0x40000
	s_addc_u32 s49, s49, 0
	global_load_lds_dwordx4 v[196:197], off
	s_mov_b32 m0, s67
	v_lshl_add_u64 v[196:197], s[48:49], 0, v[186:187]
	global_load_lds_dwordx4 v[196:197], off
	s_waitcnt vmcnt(8)
	s_waitcnt lgkmcnt(0)
	s_barrier
	s_waitcnt lgkmcnt(0)
	v_mfma_f32_16x16x32_bf16 v[66:69], v[130:133], v[162:165], v[66:69]
	v_mfma_f32_16x16x32_bf16 v[70:73], v[138:141], v[162:165], v[70:73]
	v_mfma_f32_16x16x32_bf16 v[74:77], v[130:133], v[170:173], v[74:77]
	v_mfma_f32_16x16x32_bf16 v[78:81], v[138:141], v[170:173], v[78:81]
	v_mfma_f32_16x16x32_bf16 v[86:89], v[130:133], v[178:181], v[86:89]
	v_mfma_f32_16x16x32_bf16 v[94:97], v[138:141], v[178:181], v[94:97]
	v_mfma_f32_16x16x32_bf16 v[102:105], v[130:133], v[188:191], v[102:105]
	v_mfma_f32_16x16x32_bf16 v[110:113], v[138:141], v[188:191], v[110:113]
	v_mfma_f32_16x16x32_bf16 v[66:69], v[134:137], v[166:169], v[66:69]
	v_mfma_f32_16x16x32_bf16 v[70:73], v[142:145], v[166:169], v[70:73]
	v_mfma_f32_16x16x32_bf16 v[74:77], v[134:137], v[174:177], v[74:77]
	v_mfma_f32_16x16x32_bf16 v[78:81], v[142:145], v[174:177], v[78:81]
	v_mfma_f32_16x16x32_bf16 v[86:89], v[134:137], v[182:185], v[86:89]
	v_mfma_f32_16x16x32_bf16 v[94:97], v[142:145], v[182:185], v[94:97]
	v_mfma_f32_16x16x32_bf16 v[102:105], v[134:137], v[192:195], v[102:105]
	v_mfma_f32_16x16x32_bf16 v[110:113], v[142:145], v[192:195], v[110:113]
	v_mfma_f32_16x16x32_bf16 v[82:85], v[146:149], v[162:165], v[82:85]
	v_mfma_f32_16x16x32_bf16 v[90:93], v[154:157], v[162:165], v[90:93]
	v_mfma_f32_16x16x32_bf16 v[98:101], v[146:149], v[170:173], v[98:101]
	v_mfma_f32_16x16x32_bf16 v[106:109], v[154:157], v[170:173], v[106:109]
	v_mfma_f32_16x16x32_bf16 v[114:117], v[146:149], v[178:181], v[114:117]
	v_mfma_f32_16x16x32_bf16 v[118:121], v[154:157], v[178:181], v[118:121]
	v_mfma_f32_16x16x32_bf16 v[122:125], v[146:149], v[188:191], v[122:125]
	v_mfma_f32_16x16x32_bf16 v[126:129], v[154:157], v[188:191], v[126:129]
	v_mfma_f32_16x16x32_bf16 v[82:85], v[150:153], v[166:169], v[82:85]
	v_mfma_f32_16x16x32_bf16 v[90:93], v[158:161], v[166:169], v[90:93]
	v_mfma_f32_16x16x32_bf16 v[98:101], v[150:153], v[174:177], v[98:101]
	v_mfma_f32_16x16x32_bf16 v[106:109], v[158:161], v[174:177], v[106:109]
	v_mfma_f32_16x16x32_bf16 v[114:117], v[150:153], v[182:185], v[114:117]
	v_mfma_f32_16x16x32_bf16 v[118:121], v[158:161], v[182:185], v[118:121]
	v_mfma_f32_16x16x32_bf16 v[122:125], v[150:153], v[192:195], v[122:125]
	v_mfma_f32_16x16x32_bf16 v[126:129], v[158:161], v[192:195], v[126:129]
	s_barrier
	s_add_i32 s29, s29, 2
	s_add_u32 s7, s7, 0x100
	s_addc_u32 s21, s21, 0
	s_add_u32 s27, s27, 0x100
	s_addc_u32 s28, s28, 0
	s_add_u32 s46, s46, 0x100
	s_addc_u32 s47, s47, 0
	s_cmp_gt_u32 s29, 29
	s_cbranch_scc0 .LBB0_1096
	s_setprio 0
	s_and_b64 vcc, exec, s[18:19]
	s_cbranch_vccz .LBB0_1099
	s_barrier

.LBB0_1213:
	s_add_u32 s23, s48, 0x100
	s_addc_u32 s62, s49, 0
	s_add_u32 s63, s46, 0x100
	v_mov_b32_e32 v2, 0
	s_addc_u32 s64, s47, 0
	s_mov_b32 s65, -2
	v_mov_b32_e32 v3, v2
	v_mov_b32_e32 v4, v2
	v_mov_b32_e32 v5, v2
	v_mov_b32_e32 v10, v2
	v_mov_b32_e32 v11, v2
	v_mov_b32_e32 v12, v2
	v_mov_b32_e32 v13, v2
	v_mov_b32_e32 v18, v2
	v_mov_b32_e32 v19, v2
	v_mov_b32_e32 v20, v2
	v_mov_b32_e32 v21, v2
	v_mov_b32_e32 v26, v2
	v_mov_b32_e32 v27, v2
	v_mov_b32_e32 v28, v2
	v_mov_b32_e32 v29, v2
	v_mov_b32_e32 v34, v2
	v_mov_b32_e32 v35, v2
	v_mov_b32_e32 v36, v2
	v_mov_b32_e32 v37, v2
	v_mov_b32_e32 v42, v2
	v_mov_b32_e32 v43, v2
	v_mov_b32_e32 v44, v2
	v_mov_b32_e32 v45, v2
	v_mov_b32_e32 v50, v2
	v_mov_b32_e32 v51, v2
	v_mov_b32_e32 v52, v2
	v_mov_b32_e32 v53, v2
	v_mov_b32_e32 v58, v2
	v_mov_b32_e32 v59, v2
	v_mov_b32_e32 v60, v2
	v_mov_b32_e32 v61, v2
	v_mov_b32_e32 v6, v2
	v_mov_b32_e32 v7, v2
	v_mov_b32_e32 v8, v2
	v_mov_b32_e32 v9, v2
	v_mov_b32_e32 v14, v2
	v_mov_b32_e32 v15, v2
	v_mov_b32_e32 v16, v2
	v_mov_b32_e32 v17, v2
	v_mov_b32_e32 v22, v2
	v_mov_b32_e32 v23, v2
	v_mov_b32_e32 v24, v2
	v_mov_b32_e32 v25, v2
	v_mov_b32_e32 v30, v2
	v_mov_b32_e32 v31, v2
	v_mov_b32_e32 v32, v2
	v_mov_b32_e32 v33, v2
	v_mov_b32_e32 v38, v2
	v_mov_b32_e32 v39, v2
	v_mov_b32_e32 v40, v2
	v_mov_b32_e32 v41, v2
	v_mov_b32_e32 v46, v2
	v_mov_b32_e32 v47, v2
	v_mov_b32_e32 v48, v2
	v_mov_b32_e32 v49, v2
	v_mov_b32_e32 v54, v2
	v_mov_b32_e32 v55, v2
	v_mov_b32_e32 v56, v2
	v_mov_b32_e32 v57, v2
	v_mov_b32_e32 v62, v2
	v_mov_b32_e32 v63, v2
	v_mov_b32_e32 v64, v2
	v_mov_b32_e32 v65, v2
	v_mov_b32_e32 v66, v2
	v_mov_b32_e32 v67, v2
	v_mov_b32_e32 v68, v2
	v_mov_b32_e32 v69, v2
	v_mov_b32_e32 v74, v2
	v_mov_b32_e32 v75, v2
	v_mov_b32_e32 v76, v2
	v_mov_b32_e32 v77, v2
	v_mov_b32_e32 v82, v2
	v_mov_b32_e32 v83, v2
	v_mov_b32_e32 v84, v2
	v_mov_b32_e32 v85, v2
	v_mov_b32_e32 v90, v2
	v_mov_b32_e32 v91, v2
	v_mov_b32_e32 v92, v2
	v_mov_b32_e32 v93, v2
	v_mov_b32_e32 v98, v2
	v_mov_b32_e32 v99, v2
	v_mov_b32_e32 v100, v2
	v_mov_b32_e32 v101, v2
	v_mov_b32_e32 v106, v2
	v_mov_b32_e32 v107, v2
	v_mov_b32_e32 v108, v2
	v_mov_b32_e32 v109, v2
	v_mov_b32_e32 v114, v2
	v_mov_b32_e32 v115, v2
	v_mov_b32_e32 v116, v2
	v_mov_b32_e32 v117, v2
	v_mov_b32_e32 v122, v2
	v_mov_b32_e32 v123, v2
	v_mov_b32_e32 v124, v2
	v_mov_b32_e32 v125, v2
	v_mov_b32_e32 v70, v2
	v_mov_b32_e32 v71, v2
	v_mov_b32_e32 v72, v2
	v_mov_b32_e32 v73, v2
	v_mov_b32_e32 v78, v2
	v_mov_b32_e32 v79, v2
	v_mov_b32_e32 v80, v2
	v_mov_b32_e32 v81, v2
	v_mov_b32_e32 v86, v2
	v_mov_b32_e32 v87, v2
	v_mov_b32_e32 v88, v2
	v_mov_b32_e32 v89, v2
	v_mov_b32_e32 v94, v2
	v_mov_b32_e32 v95, v2
	v_mov_b32_e32 v96, v2
	v_mov_b32_e32 v97, v2
	v_mov_b32_e32 v102, v2
	v_mov_b32_e32 v103, v2
	v_mov_b32_e32 v104, v2
	v_mov_b32_e32 v105, v2
	v_mov_b32_e32 v110, v2
	v_mov_b32_e32 v111, v2
	v_mov_b32_e32 v112, v2
	v_mov_b32_e32 v113, v2
	v_mov_b32_e32 v118, v2
	v_mov_b32_e32 v119, v2
	v_mov_b32_e32 v120, v2
	v_mov_b32_e32 v121, v2
	v_mov_b32_e32 v126, v2
	v_mov_b32_e32 v127, v2
	v_mov_b32_e32 v128, v2
	v_mov_b32_e32 v129, v2
	s_cmp_lg_u32 s18, 0
	s_cbranch_scc1 .Lsp4
	s_setprio 1
.Lsp4:
.LBB0_1214:
	s_cmp_eq_u32 s65, 12
	s_cselect_b32 s50, s42, s23
	s_cselect_b32 s51, s43, s62
	s_cselect_b32 s48, s44, s63
	s_cselect_b32 s49, s45, s64
	s_cbranch_scc0 .Lfu_nopf
	s_lshl_b32 s66, s29, 13
	s_add_u32 s66, s8, s66
	s_addc_u32 s67, s9, 0
	v_mbcnt_lo_u32_b32 v250, -1, 0
	v_mbcnt_hi_u32_b32 v250, -1, v250
	v_lshl_add_u32 v251, v250, 4, s52
	s_add_i32 m0, s52, 0x20f80
	s_nop 0
	global_load_lds_dwordx4 v251, s[66:67]
	s_lshl_b32 s66, s29, 10
	s_add_u32 s66, s10, s66
	s_addc_u32 s67, s11, 0
	v_lshlrev_b32_e32 v251, 4, v250
	s_mov_b32 m0, 0x22f80
	s_nop 0
	global_load_lds_dwordx4 v251, s[66:67]
	v_and_b32_e32 v252, 32, v250
	v_cmp_ne_u32_e64 s[66:67], 0, v252
	v_mov_b32_e32 v252, s14
	v_mov_b32_e32 v253, s15
	v_mov_b32_e32 v254, s20
	v_mov_b32_e32 v255, s21
	v_cndmask_b32_e64 v252, v252, v254, s[66:67]
	v_cndmask_b32_e64 v253, v253, v255, s[66:67]
	v_and_b32_e32 v254, 31, v250
	v_lshlrev_b32_e32 v254, 4, v254
	s_lshl_b32 s66, s28, 9
	v_add_u32_e32 v254, s66, v254
	v_mov_b32_e32 v255, 0
	v_lshl_add_u64 v[252:253], v[252:253], 0, v[254:255]
	s_mov_b32 m0, 0x23380
	s_nop 0
	global_load_lds_dwordx4 v[252:253], off
.Lfu_nopf:
	s_add_u32 s46, s50, 0x80
	s_addc_u32 s47, s51, 0
	s_add_i32 s68, 0, 0x10000
	s_add_i32 s69, 0, 0x14000
	v_add_u32_e32 v142, s68, v208
	v_add_u32_e32 v158, s69, v208
	ds_read_b128 v[130:133], v142
	ds_read_b128 v[134:137], v142 offset:1024
	ds_read_b128 v[138:141], v142 offset:2048
	ds_read_b128 v[142:145], v142 offset:3072
	ds_read_b128 v[146:149], v158
	ds_read_b128 v[150:153], v158 offset:1024
	ds_read_b128 v[154:157], v158 offset:2048
	ds_read_b128 v[158:161], v158 offset:3072
	s_add_u32 s66, s23, 0x7ff80
	s_addc_u32 s67, s62, 0
	ds_read_b128 v[162:165], v210
	ds_read_b128 v[166:169], v210 offset:1024
	ds_read_b128 v[170:173], v210 offset:2048
	ds_read_b128 v[174:177], v210 offset:3072
	ds_read_b128 v[180:183], v210 offset:4096
	ds_read_b128 v[184:187], v210 offset:5120
	ds_read_b128 v[188:191], v210 offset:6144
	ds_read_b128 v[192:195], v210 offset:7168
	s_add_i32 m0, s52, 0xc000
	v_lshl_add_u64 v[196:197], s[66:67], 0, v[178:179]
	s_add_u32 s66, s66, 0x40000
	s_addc_u32 s67, s67, 0
	global_load_lds_dwordx4 v[196:197], off
	s_add_i32 m0, s52, 0xe000
	v_lshl_add_u64 v[196:197], s[66:67], 0, v[178:179]
	global_load_lds_dwordx4 v[196:197], off
	s_waitcnt vmcnt(8)
	s_waitcnt lgkmcnt(0)
	s_barrier
	s_waitcnt lgkmcnt(0)
	v_mfma_i32_16x16x64_i8 v[126:129], v[130:133], v[162:165], v[126:129]
	v_mfma_i32_16x16x64_i8 v[118:121], v[138:141], v[162:165], v[118:121]
	v_mfma_i32_16x16x64_i8 v[110:113], v[130:133], v[170:173], v[110:113]
	v_mfma_i32_16x16x64_i8 v[102:105], v[138:141], v[170:173], v[102:105]
	v_mfma_i32_16x16x64_i8 v[94:97], v[130:133], v[180:183], v[94:97]
	v_mfma_i32_16x16x64_i8 v[86:89], v[138:141], v[180:183], v[86:89]
	v_mfma_i32_16x16x64_i8 v[78:81], v[130:133], v[188:191], v[78:81]
	v_mfma_i32_16x16x64_i8 v[70:73], v[138:141], v[188:191], v[70:73]
	v_mfma_i32_16x16x64_i8 v[126:129], v[134:137], v[166:169], v[126:129]
	v_mfma_i32_16x16x64_i8 v[118:121], v[142:145], v[166:169], v[118:121]
	v_mfma_i32_16x16x64_i8 v[110:113], v[134:137], v[174:177], v[110:113]
	v_mfma_i32_16x16x64_i8 v[102:105], v[142:145], v[174:177], v[102:105]
	v_mfma_i32_16x16x64_i8 v[94:97], v[134:137], v[184:187], v[94:97]
	v_mfma_i32_16x16x64_i8 v[86:89], v[142:145], v[184:187], v[86:89]
	v_mfma_i32_16x16x64_i8 v[78:81], v[134:137], v[192:195], v[78:81]
	v_mfma_i32_16x16x64_i8 v[70:73], v[142:145], v[192:195], v[70:73]
	v_mfma_i32_16x16x64_i8 v[122:125], v[146:149], v[162:165], v[122:125]
	v_mfma_i32_16x16x64_i8 v[114:117], v[154:157], v[162:165], v[114:117]
	v_mfma_i32_16x16x64_i8 v[106:109], v[146:149], v[170:173], v[106:109]
	v_mfma_i32_16x16x64_i8 v[98:101], v[154:157], v[170:173], v[98:101]
	v_mfma_i32_16x16x64_i8 v[90:93], v[146:149], v[180:183], v[90:93]
	v_mfma_i32_16x16x64_i8 v[82:85], v[154:157], v[180:183], v[82:85]
	v_mfma_i32_16x16x64_i8 v[74:77], v[146:149], v[188:191], v[74:77]
	v_mfma_i32_16x16x64_i8 v[66:69], v[154:157], v[188:191], v[66:69]
	v_mfma_i32_16x16x64_i8 v[122:125], v[150:153], v[166:169], v[122:125]
	v_mfma_i32_16x16x64_i8 v[114:117], v[158:161], v[166:169], v[114:117]
	v_mfma_i32_16x16x64_i8 v[106:109], v[150:153], v[174:177], v[106:109]
	v_mfma_i32_16x16x64_i8 v[98:101], v[158:161], v[174:177], v[98:101]
	v_mfma_i32_16x16x64_i8 v[90:93], v[150:153], v[184:187], v[90:93]
	v_mfma_i32_16x16x64_i8 v[82:85], v[158:161], v[184:187], v[82:85]
	v_mfma_i32_16x16x64_i8 v[74:77], v[150:153], v[192:195], v[74:77]
	v_mfma_i32_16x16x64_i8 v[66:69], v[158:161], v[192:195], v[66:69]
	s_barrier
	s_mov_b64 s[66:67], s[48:49]
	ds_read_b128 v[162:165], v210 offset:16384
	ds_read_b128 v[166:169], v210 offset:17408
	ds_read_b128 v[170:173], v210 offset:18432
	ds_read_b128 v[174:177], v210 offset:19456
	ds_read_b128 v[180:183], v210 offset:20480
	ds_read_b128 v[184:187], v210 offset:21504
	ds_read_b128 v[188:191], v210 offset:22528
	ds_read_b128 v[192:195], v210 offset:23552
	s_add_i32 s68, s68, s31
	v_lshl_add_u64 v[196:197], s[66:67], 0, v[202:203]
	s_add_u32 s66, s66, 0x20000
	s_mov_b32 m0, s68
	s_addc_u32 s67, s67, 0
	global_load_lds_dwordx4 v[196:197], off
	s_add_i32 m0, s68, 0x2000
	v_lshl_add_u64 v[196:197], s[66:67], 0, v[202:203]
	s_add_u32 s66, s48, 0x40000
	s_addc_u32 s67, s49, 0
	global_load_lds_dwordx4 v[196:197], off
	s_add_i32 s68, s69, s31
	v_lshl_add_u64 v[196:197], s[66:67], 0, v[202:203]
	s_add_u32 s66, s66, 0x20000
	s_mov_b32 m0, s68
	s_addc_u32 s67, s67, 0
	global_load_lds_dwordx4 v[196:197], off
	s_add_i32 m0, s68, 0x2000
	v_lshl_add_u64 v[196:197], s[66:67], 0, v[202:203]
	s_mov_b64 s[66:67], s[50:51]
	global_load_lds_dwordx4 v[196:197], off
	s_mov_b32 m0, s52
	v_lshl_add_u64 v[196:197], s[66:67], 0, v[178:179]
	s_add_u32 s66, s66, 0x40000
	s_addc_u32 s67, s67, 0
	global_load_lds_dwordx4 v[196:197], off
	s_mov_b32 m0, s53
	v_lshl_add_u64 v[196:197], s[66:67], 0, v[178:179]
	global_load_lds_dwordx4 v[196:197], off
	s_waitcnt vmcnt(8)
	s_waitcnt lgkmcnt(0)
	s_barrier
	s_waitcnt lgkmcnt(0)
	v_mfma_i32_16x16x64_i8 v[62:65], v[130:133], v[162:165], v[62:65]
	v_mfma_i32_16x16x64_i8 v[54:57], v[138:141], v[162:165], v[54:57]
	v_mfma_i32_16x16x64_i8 v[46:49], v[130:133], v[170:173], v[46:49]
	v_mfma_i32_16x16x64_i8 v[38:41], v[138:141], v[170:173], v[38:41]
	v_mfma_i32_16x16x64_i8 v[30:33], v[130:133], v[180:183], v[30:33]
	v_mfma_i32_16x16x64_i8 v[22:25], v[138:141], v[180:183], v[22:25]
	v_mfma_i32_16x16x64_i8 v[14:17], v[130:133], v[188:191], v[14:17]
	v_mfma_i32_16x16x64_i8 v[6:9], v[138:141], v[188:191], v[6:9]
	v_mfma_i32_16x16x64_i8 v[62:65], v[134:137], v[166:169], v[62:65]
	v_mfma_i32_16x16x64_i8 v[54:57], v[142:145], v[166:169], v[54:57]
	v_mfma_i32_16x16x64_i8 v[46:49], v[134:137], v[174:177], v[46:49]
	v_mfma_i32_16x16x64_i8 v[38:41], v[142:145], v[174:177], v[38:41]
	v_mfma_i32_16x16x64_i8 v[30:33], v[134:137], v[184:187], v[30:33]
	v_mfma_i32_16x16x64_i8 v[22:25], v[142:145], v[184:187], v[22:25]
	v_mfma_i32_16x16x64_i8 v[14:17], v[134:137], v[192:195], v[14:17]
	v_mfma_i32_16x16x64_i8 v[6:9], v[142:145], v[192:195], v[6:9]
	v_mfma_i32_16x16x64_i8 v[58:61], v[146:149], v[162:165], v[58:61]
	v_mfma_i32_16x16x64_i8 v[50:53], v[154:157], v[162:165], v[50:53]
	v_mfma_i32_16x16x64_i8 v[42:45], v[146:149], v[170:173], v[42:45]
	v_mfma_i32_16x16x64_i8 v[34:37], v[154:157], v[170:173], v[34:37]
	v_mfma_i32_16x16x64_i8 v[26:29], v[146:149], v[180:183], v[26:29]
	v_mfma_i32_16x16x64_i8 v[18:21], v[154:157], v[180:183], v[18:21]
	v_mfma_i32_16x16x64_i8 v[10:13], v[146:149], v[188:191], v[10:13]
	v_mfma_i32_16x16x64_i8 v[2:5], v[154:157], v[188:191], v[2:5]
	v_mfma_i32_16x16x64_i8 v[58:61], v[150:153], v[166:169], v[58:61]
	v_mfma_i32_16x16x64_i8 v[50:53], v[158:161], v[166:169], v[50:53]
	v_mfma_i32_16x16x64_i8 v[42:45], v[150:153], v[174:177], v[42:45]
	v_mfma_i32_16x16x64_i8 v[34:37], v[158:161], v[174:177], v[34:37]
	v_mfma_i32_16x16x64_i8 v[26:29], v[150:153], v[184:187], v[26:29]
	v_mfma_i32_16x16x64_i8 v[18:21], v[158:161], v[184:187], v[18:21]
	v_mfma_i32_16x16x64_i8 v[10:13], v[150:153], v[192:195], v[10:13]
	v_mfma_i32_16x16x64_i8 v[2:5], v[158:161], v[192:195], v[2:5]
	s_barrier
	s_add_i32 s66, 0, 0x18000
	s_add_i32 s67, 0, 0x1c000
	v_add_u32_e32 v142, s66, v208
	v_add_u32_e32 v158, s67, v208
	ds_read_b128 v[130:133], v142
	ds_read_b128 v[134:137], v142 offset:1024
	ds_read_b128 v[138:141], v142 offset:2048
	ds_read_b128 v[142:145], v142 offset:3072
	ds_read_b128 v[146:149], v158
	ds_read_b128 v[150:153], v158 offset:1024
	ds_read_b128 v[154:157], v158 offset:2048
	ds_read_b128 v[158:161], v158 offset:3072
	s_add_u32 s50, s50, 0x80000
	s_addc_u32 s51, s51, 0
	ds_read_b128 v[162:165], v210 offset:32768
	ds_read_b128 v[166:169], v210 offset:33792
	ds_read_b128 v[170:173], v210 offset:34816
	ds_read_b128 v[174:177], v210 offset:35840
	ds_read_b128 v[180:183], v210 offset:36864
	ds_read_b128 v[184:187], v210 offset:37888
	ds_read_b128 v[188:191], v210 offset:38912
	ds_read_b128 v[192:195], v210 offset:39936
	s_mov_b32 m0, s54
	v_lshl_add_u64 v[196:197], s[50:51], 0, v[178:179]
	s_add_u32 s50, s50, 0x40000
	s_addc_u32 s51, s51, 0
	global_load_lds_dwordx4 v[196:197], off
	s_mov_b32 m0, s55
	v_lshl_add_u64 v[196:197], s[50:51], 0, v[178:179]
	global_load_lds_dwordx4 v[196:197], off
	s_waitcnt vmcnt(8)
	s_waitcnt lgkmcnt(0)
	s_barrier
	s_waitcnt lgkmcnt(0)
	v_mfma_i32_16x16x64_i8 v[126:129], v[130:133], v[162:165], v[126:129]
	v_mfma_i32_16x16x64_i8 v[118:121], v[138:141], v[162:165], v[118:121]
	v_mfma_i32_16x16x64_i8 v[110:113], v[130:133], v[170:173], v[110:113]
	v_mfma_i32_16x16x64_i8 v[102:105], v[138:141], v[170:173], v[102:105]
	v_mfma_i32_16x16x64_i8 v[94:97], v[130:133], v[180:183], v[94:97]
	v_mfma_i32_16x16x64_i8 v[86:89], v[138:141], v[180:183], v[86:89]
	v_mfma_i32_16x16x64_i8 v[78:81], v[130:133], v[188:191], v[78:81]
	v_mfma_i32_16x16x64_i8 v[70:73], v[138:141], v[188:191], v[70:73]
	v_mfma_i32_16x16x64_i8 v[126:129], v[134:137], v[166:169], v[126:129]
	v_mfma_i32_16x16x64_i8 v[118:121], v[142:145], v[166:169], v[118:121]
	v_mfma_i32_16x16x64_i8 v[110:113], v[134:137], v[174:177], v[110:113]
	v_mfma_i32_16x16x64_i8 v[102:105], v[142:145], v[174:177], v[102:105]
	v_mfma_i32_16x16x64_i8 v[94:97], v[134:137], v[184:187], v[94:97]
	v_mfma_i32_16x16x64_i8 v[86:89], v[142:145], v[184:187], v[86:89]
	v_mfma_i32_16x16x64_i8 v[78:81], v[134:137], v[192:195], v[78:81]
	v_mfma_i32_16x16x64_i8 v[70:73], v[142:145], v[192:195], v[70:73]
	v_mfma_i32_16x16x64_i8 v[122:125], v[146:149], v[162:165], v[122:125]
	v_mfma_i32_16x16x64_i8 v[114:117], v[154:157], v[162:165], v[114:117]
	v_mfma_i32_16x16x64_i8 v[106:109], v[146:149], v[170:173], v[106:109]
	v_mfma_i32_16x16x64_i8 v[98:101], v[154:157], v[170:173], v[98:101]
	v_mfma_i32_16x16x64_i8 v[90:93], v[146:149], v[180:183], v[90:93]
	v_mfma_i32_16x16x64_i8 v[82:85], v[154:157], v[180:183], v[82:85]
	v_mfma_i32_16x16x64_i8 v[74:77], v[146:149], v[188:191], v[74:77]
	v_mfma_i32_16x16x64_i8 v[66:69], v[154:157], v[188:191], v[66:69]
	v_mfma_i32_16x16x64_i8 v[122:125], v[150:153], v[166:169], v[122:125]
	v_mfma_i32_16x16x64_i8 v[114:117], v[158:161], v[166:169], v[114:117]
	v_mfma_i32_16x16x64_i8 v[106:109], v[150:153], v[174:177], v[106:109]
	v_mfma_i32_16x16x64_i8 v[98:101], v[158:161], v[174:177], v[98:101]
	v_mfma_i32_16x16x64_i8 v[90:93], v[150:153], v[184:187], v[90:93]
	v_mfma_i32_16x16x64_i8 v[82:85], v[158:161], v[184:187], v[82:85]
	v_mfma_i32_16x16x64_i8 v[74:77], v[150:153], v[192:195], v[74:77]
	v_mfma_i32_16x16x64_i8 v[66:69], v[158:161], v[192:195], v[66:69]
	s_barrier
	s_add_u32 s50, s48, 0x80
	s_addc_u32 s51, s49, 0
	ds_read_b128 v[162:165], v210 offset:49152
	ds_read_b128 v[166:169], v210 offset:50176
	ds_read_b128 v[170:173], v210 offset:51200
	ds_read_b128 v[174:177], v210 offset:52224
	ds_read_b128 v[180:183], v210 offset:53248
	ds_read_b128 v[184:187], v210 offset:54272
	ds_read_b128 v[188:191], v210 offset:55296
	ds_read_b128 v[192:195], v210 offset:56320
	s_add_i32 s66, s66, s31
	v_lshl_add_u64 v[196:197], s[50:51], 0, v[202:203]
	s_mov_b32 m0, s66
	s_add_u32 s50, s50, 0x20000
	global_load_lds_dwordx4 v[196:197], off
	s_addc_u32 s51, s51, 0
	s_add_i32 m0, s66, 0x2000
	s_add_u32 s48, s48, 0x40080
	s_addc_u32 s49, s49, 0
	v_lshl_add_u64 v[196:197], s[50:51], 0, v[202:203]
	global_load_lds_dwordx4 v[196:197], off
	s_add_i32 s50, s67, s31
	v_lshl_add_u64 v[196:197], s[48:49], 0, v[202:203]
	s_add_u32 s48, s48, 0x20000
	s_mov_b32 m0, s50
	s_addc_u32 s49, s49, 0
	global_load_lds_dwordx4 v[196:197], off
	s_add_i32 m0, s50, 0x2000
	v_lshl_add_u64 v[196:197], s[48:49], 0, v[202:203]
	global_load_lds_dwordx4 v[196:197], off
	s_mov_b32 m0, s56
	v_lshl_add_u64 v[196:197], s[46:47], 0, v[178:179]
	s_add_u32 s46, s46, 0x40000
	s_addc_u32 s47, s47, 0
	global_load_lds_dwordx4 v[196:197], off
	s_mov_b32 m0, s57
	v_lshl_add_u64 v[196:197], s[46:47], 0, v[178:179]
	global_load_lds_dwordx4 v[196:197], off
	s_waitcnt vmcnt(8)
	s_waitcnt lgkmcnt(0)
	s_barrier
	s_waitcnt lgkmcnt(0)
	v_mfma_i32_16x16x64_i8 v[62:65], v[130:133], v[162:165], v[62:65]
	v_mfma_i32_16x16x64_i8 v[54:57], v[138:141], v[162:165], v[54:57]
	v_mfma_i32_16x16x64_i8 v[46:49], v[130:133], v[170:173], v[46:49]
	v_mfma_i32_16x16x64_i8 v[38:41], v[138:141], v[170:173], v[38:41]
	v_mfma_i32_16x16x64_i8 v[30:33], v[130:133], v[180:183], v[30:33]
	v_mfma_i32_16x16x64_i8 v[22:25], v[138:141], v[180:183], v[22:25]
	v_mfma_i32_16x16x64_i8 v[14:17], v[130:133], v[188:191], v[14:17]
	v_mfma_i32_16x16x64_i8 v[6:9], v[138:141], v[188:191], v[6:9]
	v_mfma_i32_16x16x64_i8 v[62:65], v[134:137], v[166:169], v[62:65]
	v_mfma_i32_16x16x64_i8 v[54:57], v[142:145], v[166:169], v[54:57]
	v_mfma_i32_16x16x64_i8 v[46:49], v[134:137], v[174:177], v[46:49]
	v_mfma_i32_16x16x64_i8 v[38:41], v[142:145], v[174:177], v[38:41]
	v_mfma_i32_16x16x64_i8 v[30:33], v[134:137], v[184:187], v[30:33]
	v_mfma_i32_16x16x64_i8 v[22:25], v[142:145], v[184:187], v[22:25]
	v_mfma_i32_16x16x64_i8 v[14:17], v[134:137], v[192:195], v[14:17]
	v_mfma_i32_16x16x64_i8 v[6:9], v[142:145], v[192:195], v[6:9]
	v_mfma_i32_16x16x64_i8 v[58:61], v[146:149], v[162:165], v[58:61]
	v_mfma_i32_16x16x64_i8 v[50:53], v[154:157], v[162:165], v[50:53]
	v_mfma_i32_16x16x64_i8 v[42:45], v[146:149], v[170:173], v[42:45]
	v_mfma_i32_16x16x64_i8 v[34:37], v[154:157], v[170:173], v[34:37]
	v_mfma_i32_16x16x64_i8 v[26:29], v[146:149], v[180:183], v[26:29]
	v_mfma_i32_16x16x64_i8 v[18:21], v[154:157], v[180:183], v[18:21]
	v_mfma_i32_16x16x64_i8 v[10:13], v[146:149], v[188:191], v[10:13]
	v_mfma_i32_16x16x64_i8 v[2:5], v[154:157], v[188:191], v[2:5]
	v_mfma_i32_16x16x64_i8 v[58:61], v[150:153], v[166:169], v[58:61]
	v_mfma_i32_16x16x64_i8 v[50:53], v[158:161], v[166:169], v[50:53]
	v_mfma_i32_16x16x64_i8 v[42:45], v[150:153], v[174:177], v[42:45]
	v_mfma_i32_16x16x64_i8 v[34:37], v[158:161], v[174:177], v[34:37]
	v_mfma_i32_16x16x64_i8 v[26:29], v[150:153], v[184:187], v[26:29]
	v_mfma_i32_16x16x64_i8 v[18:21], v[158:161], v[184:187], v[18:21]
	v_mfma_i32_16x16x64_i8 v[10:13], v[150:153], v[192:195], v[10:13]
	v_mfma_i32_16x16x64_i8 v[2:5], v[158:161], v[192:195], v[2:5]
	s_barrier
	s_add_i32 s65, s65, 2
	s_add_u32 s23, s23, 0x100
	s_addc_u32 s62, s62, 0
	s_add_u32 s63, s63, 0x100
	s_addc_u32 s64, s64, 0
	s_cmp_gt_u32 s65, 13
	s_cbranch_scc0 .LBB0_1214
	s_setprio 0
	s_and_b64 vcc, exec, s[18:19]
	s_cbranch_vccz .LBB0_1217
	s_barrier

.LBB0_1285:
	s_add_u32 s9, s44, 0x100
	s_addc_u32 s27, s45, 0
	s_add_u32 s28, s46, 0x100
	s_addc_u32 s29, s47, 0
	s_add_u32 s44, s44, 0x160080
	s_addc_u32 s45, s45, 0
	s_mov_b32 s71, -2
	s_cmp_lg_u32 s18, 0
	s_cbranch_scc1 .Lsp5
	s_setprio 1
.Lsp5:
.LBB0_1286:
	s_cmpk_eq_i32 s71, 0x54
	s_cselect_b32 s54, s48, s9
	s_cselect_b32 s55, s49, s27
	s_cselect_b32 s52, s50, s28
	s_cselect_b32 s53, s51, s29
	s_add_u32 s46, s54, 0x80
	s_addc_u32 s47, s55, 0
	s_add_i32 s74, 0, 0x10000
	s_add_i32 s75, 0, 0x14000
	v_add_u32_e32 v142, s74, v207
	v_add_u32_e32 v158, s75, v207
	s_waitcnt lgkmcnt(0)
	s_cmpk_eq_i32 s71, 0x54
	s_cbranch_scc0 .Lfd_nopf
	s_lshl_b32 s72, s8, 13
	s_add_u32 s72, s14, s72
	s_addc_u32 s73, s15, 0
	v_mbcnt_lo_u32_b32 v250, -1, 0
	v_mbcnt_hi_u32_b32 v250, -1, v250
	v_lshl_add_u32 v250, v250, 4, s58
	s_add_i32 m0, s58, 0x24f80
	s_nop 0
	global_load_lds_dwordx4 v250, s[72:73]
.Lfd_nopf:
	ds_read_b128 v[130:133], v142
	ds_read_b128 v[134:137], v142 offset:1024
	ds_read_b128 v[138:141], v142 offset:2048
	ds_read_b128 v[142:145], v142 offset:3072
	ds_read_b128 v[146:149], v158
	ds_read_b128 v[150:153], v158 offset:1024
	ds_read_b128 v[154:157], v158 offset:2048
	ds_read_b128 v[158:161], v158 offset:3072
	s_mov_b64 s[72:73], s[44:45]
	ds_read_b128 v[162:165], v237
	ds_read_b128 v[166:169], v237 offset:1024
	ds_read_b128 v[170:173], v237 offset:2048
	ds_read_b128 v[174:177], v237 offset:3072
	ds_read_b128 v[178:181], v237 offset:4096
	ds_read_b128 v[182:185], v237 offset:5120
	ds_read_b128 v[188:191], v237 offset:6144
	ds_read_b128 v[192:195], v237 offset:7168
	s_add_i32 m0, s58, 0xc000
	v_lshl_add_u64 v[196:197], s[72:73], 0, v[186:187]
	s_add_u32 s72, s72, 0xb0000
	s_addc_u32 s73, s73, 0
	global_load_lds_dwordx4 v[196:197], off
	s_add_i32 m0, s58, 0xe000
	v_lshl_add_u64 v[196:197], s[72:73], 0, v[186:187]
	global_load_lds_dwordx4 v[196:197], off
	s_waitcnt vmcnt(8)
	s_waitcnt lgkmcnt(0)
	s_barrier
	s_waitcnt lgkmcnt(0)
	v_mfma_f32_16x16x32_bf16 v[2:5], v[130:133], v[162:165], v[2:5]
	v_mfma_f32_16x16x32_bf16 v[6:9], v[138:141], v[162:165], v[6:9]
	v_mfma_f32_16x16x32_bf16 v[14:17], v[130:133], v[170:173], v[14:17]
	v_mfma_f32_16x16x32_bf16 v[22:25], v[138:141], v[170:173], v[22:25]
	v_mfma_f32_16x16x32_bf16 v[30:33], v[130:133], v[178:181], v[30:33]
	v_mfma_f32_16x16x32_bf16 v[38:41], v[138:141], v[178:181], v[38:41]
	v_mfma_f32_16x16x32_bf16 v[46:49], v[130:133], v[188:191], v[46:49]
	v_mfma_f32_16x16x32_bf16 v[54:57], v[138:141], v[188:191], v[54:57]
	v_mfma_f32_16x16x32_bf16 v[2:5], v[134:137], v[166:169], v[2:5]
	v_mfma_f32_16x16x32_bf16 v[6:9], v[142:145], v[166:169], v[6:9]
	v_mfma_f32_16x16x32_bf16 v[14:17], v[134:137], v[174:177], v[14:17]
	v_mfma_f32_16x16x32_bf16 v[22:25], v[142:145], v[174:177], v[22:25]
	v_mfma_f32_16x16x32_bf16 v[30:33], v[134:137], v[182:185], v[30:33]
	v_mfma_f32_16x16x32_bf16 v[38:41], v[142:145], v[182:185], v[38:41]
	v_mfma_f32_16x16x32_bf16 v[46:49], v[134:137], v[192:195], v[46:49]
	v_mfma_f32_16x16x32_bf16 v[54:57], v[142:145], v[192:195], v[54:57]
	v_mfma_f32_16x16x32_bf16 v[10:13], v[146:149], v[162:165], v[10:13]
	v_mfma_f32_16x16x32_bf16 v[18:21], v[154:157], v[162:165], v[18:21]
	v_mfma_f32_16x16x32_bf16 v[26:29], v[146:149], v[170:173], v[26:29]
	v_mfma_f32_16x16x32_bf16 v[34:37], v[154:157], v[170:173], v[34:37]
	v_mfma_f32_16x16x32_bf16 v[42:45], v[146:149], v[178:181], v[42:45]
	v_mfma_f32_16x16x32_bf16 v[50:53], v[154:157], v[178:181], v[50:53]
	v_mfma_f32_16x16x32_bf16 v[58:61], v[146:149], v[188:191], v[58:61]
	v_mfma_f32_16x16x32_bf16 v[62:65], v[154:157], v[188:191], v[62:65]
	v_mfma_f32_16x16x32_bf16 v[10:13], v[150:153], v[166:169], v[10:13]
	v_mfma_f32_16x16x32_bf16 v[18:21], v[158:161], v[166:169], v[18:21]
	v_mfma_f32_16x16x32_bf16 v[26:29], v[150:153], v[174:177], v[26:29]
	v_mfma_f32_16x16x32_bf16 v[34:37], v[158:161], v[174:177], v[34:37]
	v_mfma_f32_16x16x32_bf16 v[42:45], v[150:153], v[182:185], v[42:45]
	v_mfma_f32_16x16x32_bf16 v[50:53], v[158:161], v[182:185], v[50:53]
	v_mfma_f32_16x16x32_bf16 v[58:61], v[150:153], v[192:195], v[58:61]
	v_mfma_f32_16x16x32_bf16 v[62:65], v[158:161], v[192:195], v[62:65]
	s_barrier
	s_mov_b64 s[72:73], s[52:53]
	ds_read_b128 v[162:165], v237 offset:16384
	ds_read_b128 v[166:169], v237 offset:17408
	ds_read_b128 v[170:173], v237 offset:18432
	ds_read_b128 v[174:177], v237 offset:19456
	ds_read_b128 v[178:181], v237 offset:20480
	ds_read_b128 v[182:185], v237 offset:21504
	ds_read_b128 v[188:191], v237 offset:22528
	ds_read_b128 v[192:195], v237 offset:23552
	s_add_i32 s74, s74, s57
	v_lshl_add_u64 v[196:197], s[72:73], 0, v[202:203]
	s_add_u32 s72, s72, 0xb0000
	s_mov_b32 m0, s74
	s_addc_u32 s73, s73, 0
	global_load_lds_dwordx4 v[196:197], off
	s_add_i32 m0, s74, 0x2000
	v_lshl_add_u64 v[196:197], s[72:73], 0, v[202:203]
	s_add_u32 s72, s52, 0x160000
	s_addc_u32 s73, s53, 0
	global_load_lds_dwordx4 v[196:197], off
	s_add_i32 s74, s75, s57
	v_lshl_add_u64 v[196:197], s[72:73], 0, v[202:203]
	s_add_u32 s72, s72, 0xb0000
	s_mov_b32 m0, s74
	s_addc_u32 s73, s73, 0
	global_load_lds_dwordx4 v[196:197], off
	s_add_i32 m0, s74, 0x2000
	v_lshl_add_u64 v[196:197], s[72:73], 0, v[202:203]
	s_mov_b64 s[72:73], s[54:55]
	global_load_lds_dwordx4 v[196:197], off
	s_mov_b32 m0, s58
	v_lshl_add_u64 v[196:197], s[72:73], 0, v[186:187]
	s_add_u32 s72, s72, 0xb0000
	s_addc_u32 s73, s73, 0
	global_load_lds_dwordx4 v[196:197], off
	s_mov_b32 m0, s59
	v_lshl_add_u64 v[196:197], s[72:73], 0, v[186:187]
	global_load_lds_dwordx4 v[196:197], off
	s_waitcnt vmcnt(8)
	s_waitcnt lgkmcnt(0)
	s_barrier
	s_waitcnt lgkmcnt(0)
	v_mfma_f32_16x16x32_bf16 v[66:69], v[130:133], v[162:165], v[66:69]
	v_mfma_f32_16x16x32_bf16 v[70:73], v[138:141], v[162:165], v[70:73]
	v_mfma_f32_16x16x32_bf16 v[74:77], v[130:133], v[170:173], v[74:77]
	v_mfma_f32_16x16x32_bf16 v[78:81], v[138:141], v[170:173], v[78:81]
	v_mfma_f32_16x16x32_bf16 v[86:89], v[130:133], v[178:181], v[86:89]
	v_mfma_f32_16x16x32_bf16 v[94:97], v[138:141], v[178:181], v[94:97]
	v_mfma_f32_16x16x32_bf16 v[102:105], v[130:133], v[188:191], v[102:105]
	v_mfma_f32_16x16x32_bf16 v[110:113], v[138:141], v[188:191], v[110:113]
	v_mfma_f32_16x16x32_bf16 v[66:69], v[134:137], v[166:169], v[66:69]
	v_mfma_f32_16x16x32_bf16 v[70:73], v[142:145], v[166:169], v[70:73]
	v_mfma_f32_16x16x32_bf16 v[74:77], v[134:137], v[174:177], v[74:77]
	v_mfma_f32_16x16x32_bf16 v[78:81], v[142:145], v[174:177], v[78:81]
	v_mfma_f32_16x16x32_bf16 v[86:89], v[134:137], v[182:185], v[86:89]
	v_mfma_f32_16x16x32_bf16 v[94:97], v[142:145], v[182:185], v[94:97]
	v_mfma_f32_16x16x32_bf16 v[102:105], v[134:137], v[192:195], v[102:105]
	v_mfma_f32_16x16x32_bf16 v[110:113], v[142:145], v[192:195], v[110:113]
	v_mfma_f32_16x16x32_bf16 v[82:85], v[146:149], v[162:165], v[82:85]
	v_mfma_f32_16x16x32_bf16 v[90:93], v[154:157], v[162:165], v[90:93]
	v_mfma_f32_16x16x32_bf16 v[98:101], v[146:149], v[170:173], v[98:101]
	v_mfma_f32_16x16x32_bf16 v[106:109], v[154:157], v[170:173], v[106:109]
	v_mfma_f32_16x16x32_bf16 v[114:117], v[146:149], v[178:181], v[114:117]
	v_mfma_f32_16x16x32_bf16 v[118:121], v[154:157], v[178:181], v[118:121]
	v_mfma_f32_16x16x32_bf16 v[122:125], v[146:149], v[188:191], v[122:125]
	v_mfma_f32_16x16x32_bf16 v[126:129], v[154:157], v[188:191], v[126:129]
	v_mfma_f32_16x16x32_bf16 v[82:85], v[150:153], v[166:169], v[82:85]
	v_mfma_f32_16x16x32_bf16 v[90:93], v[158:161], v[166:169], v[90:93]
	v_mfma_f32_16x16x32_bf16 v[98:101], v[150:153], v[174:177], v[98:101]
	v_mfma_f32_16x16x32_bf16 v[106:109], v[158:161], v[174:177], v[106:109]
	v_mfma_f32_16x16x32_bf16 v[114:117], v[150:153], v[182:185], v[114:117]
	v_mfma_f32_16x16x32_bf16 v[118:121], v[158:161], v[182:185], v[118:121]
	v_mfma_f32_16x16x32_bf16 v[122:125], v[150:153], v[192:195], v[122:125]
	v_mfma_f32_16x16x32_bf16 v[126:129], v[158:161], v[192:195], v[126:129]
	s_barrier
	s_add_i32 s72, 0, 0x18000
	s_add_i32 s73, 0, 0x1c000
	v_add_u32_e32 v142, s72, v207
	v_add_u32_e32 v158, s73, v207
	ds_read_b128 v[130:133], v142
	ds_read_b128 v[134:137], v142 offset:1024
	ds_read_b128 v[138:141], v142 offset:2048
	ds_read_b128 v[142:145], v142 offset:3072
	ds_read_b128 v[146:149], v158
	ds_read_b128 v[150:153], v158 offset:1024
	ds_read_b128 v[154:157], v158 offset:2048
	ds_read_b128 v[158:161], v158 offset:3072
	s_add_u32 s54, s54, 0x160000
	s_addc_u32 s55, s55, 0
	ds_read_b128 v[162:165], v237 offset:32768
	ds_read_b128 v[166:169], v237 offset:33792
	ds_read_b128 v[170:173], v237 offset:34816
	ds_read_b128 v[174:177], v237 offset:35840
	ds_read_b128 v[178:181], v237 offset:36864
	ds_read_b128 v[182:185], v237 offset:37888
	ds_read_b128 v[188:191], v237 offset:38912
	ds_read_b128 v[192:195], v237 offset:39936
	s_mov_b32 m0, s60
	v_lshl_add_u64 v[196:197], s[54:55], 0, v[186:187]
	s_add_u32 s54, s54, 0xb0000
	s_addc_u32 s55, s55, 0
	global_load_lds_dwordx4 v[196:197], off
	s_mov_b32 m0, s61
	v_lshl_add_u64 v[196:197], s[54:55], 0, v[186:187]
	global_load_lds_dwordx4 v[196:197], off
	s_waitcnt vmcnt(8)
	s_waitcnt lgkmcnt(0)
	s_barrier
	s_waitcnt lgkmcnt(0)
	v_mfma_f32_16x16x32_bf16 v[2:5], v[130:133], v[162:165], v[2:5]
	v_mfma_f32_16x16x32_bf16 v[6:9], v[138:141], v[162:165], v[6:9]
	v_mfma_f32_16x16x32_bf16 v[14:17], v[130:133], v[170:173], v[14:17]
	v_mfma_f32_16x16x32_bf16 v[22:25], v[138:141], v[170:173], v[22:25]
	v_mfma_f32_16x16x32_bf16 v[30:33], v[130:133], v[178:181], v[30:33]
	v_mfma_f32_16x16x32_bf16 v[38:41], v[138:141], v[178:181], v[38:41]
	v_mfma_f32_16x16x32_bf16 v[46:49], v[130:133], v[188:191], v[46:49]
	v_mfma_f32_16x16x32_bf16 v[54:57], v[138:141], v[188:191], v[54:57]
	v_mfma_f32_16x16x32_bf16 v[2:5], v[134:137], v[166:169], v[2:5]
	v_mfma_f32_16x16x32_bf16 v[6:9], v[142:145], v[166:169], v[6:9]
	v_mfma_f32_16x16x32_bf16 v[14:17], v[134:137], v[174:177], v[14:17]
	v_mfma_f32_16x16x32_bf16 v[22:25], v[142:145], v[174:177], v[22:25]
	v_mfma_f32_16x16x32_bf16 v[30:33], v[134:137], v[182:185], v[30:33]
	v_mfma_f32_16x16x32_bf16 v[38:41], v[142:145], v[182:185], v[38:41]
	v_mfma_f32_16x16x32_bf16 v[46:49], v[134:137], v[192:195], v[46:49]
	v_mfma_f32_16x16x32_bf16 v[54:57], v[142:145], v[192:195], v[54:57]
	v_mfma_f32_16x16x32_bf16 v[10:13], v[146:149], v[162:165], v[10:13]
	v_mfma_f32_16x16x32_bf16 v[18:21], v[154:157], v[162:165], v[18:21]
	v_mfma_f32_16x16x32_bf16 v[26:29], v[146:149], v[170:173], v[26:29]
	v_mfma_f32_16x16x32_bf16 v[34:37], v[154:157], v[170:173], v[34:37]
	v_mfma_f32_16x16x32_bf16 v[42:45], v[146:149], v[178:181], v[42:45]
	v_mfma_f32_16x16x32_bf16 v[50:53], v[154:157], v[178:181], v[50:53]
	v_mfma_f32_16x16x32_bf16 v[58:61], v[146:149], v[188:191], v[58:61]
	v_mfma_f32_16x16x32_bf16 v[62:65], v[154:157], v[188:191], v[62:65]
	v_mfma_f32_16x16x32_bf16 v[10:13], v[150:153], v[166:169], v[10:13]
	v_mfma_f32_16x16x32_bf16 v[18:21], v[158:161], v[166:169], v[18:21]
	v_mfma_f32_16x16x32_bf16 v[26:29], v[150:153], v[174:177], v[26:29]
	v_mfma_f32_16x16x32_bf16 v[34:37], v[158:161], v[174:177], v[34:37]
	v_mfma_f32_16x16x32_bf16 v[42:45], v[150:153], v[182:185], v[42:45]
	v_mfma_f32_16x16x32_bf16 v[50:53], v[158:161], v[182:185], v[50:53]
	v_mfma_f32_16x16x32_bf16 v[58:61], v[150:153], v[192:195], v[58:61]
	v_mfma_f32_16x16x32_bf16 v[62:65], v[158:161], v[192:195], v[62:65]
	s_barrier
	s_add_u32 s54, s52, 0x80
	s_addc_u32 s55, s53, 0
	ds_read_b128 v[162:165], v237 offset:49152
	ds_read_b128 v[166:169], v237 offset:50176
	ds_read_b128 v[170:173], v237 offset:51200
	ds_read_b128 v[174:177], v237 offset:52224
	ds_read_b128 v[178:181], v237 offset:53248
	ds_read_b128 v[182:185], v237 offset:54272
	ds_read_b128 v[188:191], v237 offset:55296
	ds_read_b128 v[192:195], v237 offset:56320
	s_add_i32 s72, s72, s57
	v_lshl_add_u64 v[196:197], s[54:55], 0, v[202:203]
	s_mov_b32 m0, s72
	s_add_u32 s54, s54, 0xb0000
	global_load_lds_dwordx4 v[196:197], off
	s_addc_u32 s55, s55, 0
	s_add_i32 m0, s72, 0x2000
	s_add_u32 s52, s52, 0x160080
	s_addc_u32 s53, s53, 0
	v_lshl_add_u64 v[196:197], s[54:55], 0, v[202:203]
	global_load_lds_dwordx4 v[196:197], off
	s_add_i32 s54, s73, s57
	v_lshl_add_u64 v[196:197], s[52:53], 0, v[202:203]
	s_add_u32 s52, s52, 0xb0000
	s_mov_b32 m0, s54
	s_addc_u32 s53, s53, 0
	global_load_lds_dwordx4 v[196:197], off
	s_add_i32 m0, s54, 0x2000
	v_lshl_add_u64 v[196:197], s[52:53], 0, v[202:203]
	global_load_lds_dwordx4 v[196:197], off
	s_mov_b32 m0, s62
	v_lshl_add_u64 v[196:197], s[46:47], 0, v[186:187]
	s_add_u32 s46, s46, 0xb0000
	s_addc_u32 s47, s47, 0
	global_load_lds_dwordx4 v[196:197], off
	s_mov_b32 m0, s63
	v_lshl_add_u64 v[196:197], s[46:47], 0, v[186:187]
	global_load_lds_dwordx4 v[196:197], off
	s_waitcnt vmcnt(8)
	s_waitcnt lgkmcnt(0)
	s_barrier
	s_waitcnt lgkmcnt(0)
	v_mfma_f32_16x16x32_bf16 v[66:69], v[130:133], v[162:165], v[66:69]
	v_mfma_f32_16x16x32_bf16 v[70:73], v[138:141], v[162:165], v[70:73]
	v_mfma_f32_16x16x32_bf16 v[74:77], v[130:133], v[170:173], v[74:77]
	v_mfma_f32_16x16x32_bf16 v[78:81], v[138:141], v[170:173], v[78:81]
	v_mfma_f32_16x16x32_bf16 v[86:89], v[130:133], v[178:181], v[86:89]
	v_mfma_f32_16x16x32_bf16 v[94:97], v[138:141], v[178:181], v[94:97]
	v_mfma_f32_16x16x32_bf16 v[102:105], v[130:133], v[188:191], v[102:105]
	v_mfma_f32_16x16x32_bf16 v[110:113], v[138:141], v[188:191], v[110:113]
	v_mfma_f32_16x16x32_bf16 v[66:69], v[134:137], v[166:169], v[66:69]
	v_mfma_f32_16x16x32_bf16 v[70:73], v[142:145], v[166:169], v[70:73]
	v_mfma_f32_16x16x32_bf16 v[74:77], v[134:137], v[174:177], v[74:77]
	v_mfma_f32_16x16x32_bf16 v[78:81], v[142:145], v[174:177], v[78:81]
	v_mfma_f32_16x16x32_bf16 v[86:89], v[134:137], v[182:185], v[86:89]
	v_mfma_f32_16x16x32_bf16 v[94:97], v[142:145], v[182:185], v[94:97]
	v_mfma_f32_16x16x32_bf16 v[102:105], v[134:137], v[192:195], v[102:105]
	v_mfma_f32_16x16x32_bf16 v[110:113], v[142:145], v[192:195], v[110:113]
	v_mfma_f32_16x16x32_bf16 v[82:85], v[146:149], v[162:165], v[82:85]
	v_mfma_f32_16x16x32_bf16 v[90:93], v[154:157], v[162:165], v[90:93]
	v_mfma_f32_16x16x32_bf16 v[98:101], v[146:149], v[170:173], v[98:101]
	v_mfma_f32_16x16x32_bf16 v[106:109], v[154:157], v[170:173], v[106:109]
	v_mfma_f32_16x16x32_bf16 v[114:117], v[146:149], v[178:181], v[114:117]
	v_mfma_f32_16x16x32_bf16 v[118:121], v[154:157], v[178:181], v[118:121]
	v_mfma_f32_16x16x32_bf16 v[122:125], v[146:149], v[188:191], v[122:125]
	v_mfma_f32_16x16x32_bf16 v[126:129], v[154:157], v[188:191], v[126:129]
	v_mfma_f32_16x16x32_bf16 v[82:85], v[150:153], v[166:169], v[82:85]
	v_mfma_f32_16x16x32_bf16 v[90:93], v[158:161], v[166:169], v[90:93]
	v_mfma_f32_16x16x32_bf16 v[98:101], v[150:153], v[174:177], v[98:101]
	v_mfma_f32_16x16x32_bf16 v[106:109], v[158:161], v[174:177], v[106:109]
	v_mfma_f32_16x16x32_bf16 v[114:117], v[150:153], v[182:185], v[114:117]
	v_mfma_f32_16x16x32_bf16 v[118:121], v[158:161], v[182:185], v[118:121]
	v_mfma_f32_16x16x32_bf16 v[122:125], v[150:153], v[192:195], v[122:125]
	v_mfma_f32_16x16x32_bf16 v[126:129], v[158:161], v[192:195], v[126:129]
	s_barrier
	s_add_i32 s71, s71, 2
	s_add_u32 s9, s9, 0x100
	s_addc_u32 s27, s27, 0
	s_add_u32 s28, s28, 0x100
	s_addc_u32 s29, s29, 0
	s_add_u32 s44, s44, 0x100
	s_addc_u32 s45, s45, 0
	s_cmpk_gt_u32 s71, 0x55
	s_cbranch_scc0 .LBB0_1286
	s_setprio 0
	s_and_b64 vcc, exec, s[18:19]
	s_cbranch_vccz .LBB0_1289
	s_barrier
